# attention loop: K/V LDS-DMA issue and next-tile K fragment reads moved into MFMA shadows
# baseline (speedup 1.0000x reference)
; #define LAS __attribute__((address_space(3)))
; __device__ __forceinline__ void attn_block(LAS unsigned char* lds, const bf16_t* P, bf16_t* mix, int b, int h, int qb, float lam, float outscale, const float* subln) {
;     ...
;     for (int kt = 0; kt < ntiles; ++kt) {
;         __syncthreads();
;         const int buf = kt & 1;
;         if (kt + 1 < ntiles) {
;             const size_t ro = (size_t)(64 * (kt + 1)) * INC;
;             kr0 = *(const u32x4*)(kg + ro + (size_t)srow * INC); kr1 = *(const u32x4*)(kg + ro + (size_t)(srow + 32) * INC);
;             vr0 = *(const u32x4*)(vg + ro + (size_t)srow * INC); vr1 = *(const u32x4*)(vg + ro + (size_t)(srow + 32) * INC);
;         }
;         const int kb = 64 * kt;
;         if (kb <= qw0 + 31) {
;             LAS const unsigned char* Kb = lds + ATT_K0 + buf * 16384;
;             LAS const unsigned char* Vb = lds + ATT_V0 + buf * 16384;
;             f32x16 s0, s1;
; #pragma unroll
;             for (int j = 0; j < 16; ++j) { s0[j] = 0.f; s1[j] = 0.f; }
;             bf16x8 ka[4][2];
; #pragma unroll
;             for (int ks = 0; ks < 4; ++ks) { ka[ks][0] = *(const LAS bf16x8*)(Kb + kbase[ks]); ka[ks][1] = *(const LAS bf16x8*)(Kb + kbase[ks] + 8192); }
;             __builtin_amdgcn_sched_barrier(0);
; #pragma unroll
;             for (int ks = 0; ks < 4; ++ks) {
;                 s0 = __builtin_amdgcn_mfma_f32_32x32x16_bf16(ka[ks][0], qf[ks], s0, 0, 0, 0);
;                 s1 = __builtin_amdgcn_mfma_f32_32x32x16_bf16(ka[ks][1], qf[ks], s1, 0, 0, 0);
;             }
;             if (kb + 63 > qw0) {
; #pragma unroll
;                 for (int j = 0; j < 16; ++j) { const int key = kb + crow(j, hi); if (key > qrow) s0[j] = -INFINITY; if (key + 32 > qrow) s1[j] = -INFINITY; }
;             }
;             float mxa = max3f(s0[0], s1[0], s0[1]), mxb = max3f(s1[1], s0[2], s1[2]), mxc = max3f(s0[3], s1[3], s0[4]), mxd = max3f(s1[4], s0[5], s1[5]);
;             mxa = max3f(mxa, s0[6], s1[6]); mxb = max3f(mxb, s0[7], s1[7]); mxc = max3f(mxc, s0[8], s1[8]); mxd = max3f(mxd, s0[9], s1[9]);
;             mxa = max3f(mxa, s0[10], s1[10]); mxb = max3f(mxb, s0[11], s1[11]); mxc = max3f(mxc, s0[12], s1[12]); mxd = max3f(mxd, s0[13], s1[13]);
;             mxa = max3f(mxa, s0[14], s1[14]); mxb = max3f(mxb, s0[15], s1[15]);
;             float mx = max3f(mxa, mxb, max3f(mxc, mxd, mxd));
.Lat1_U_top:
	s_waitcnt lgkmcnt(6)
	v_mfma_f32_32x32x16_bf16 v[82:97], v[136:139], v[110:113], v[222:237]
	v_mfma_f32_32x32x16_bf16 v[66:81], v[140:143], v[110:113], v[222:237]
	s_waitcnt lgkmcnt(4)
	v_mfma_f32_32x32x16_bf16 v[82:97], v[204:207], v[106:109], v[82:97]
	v_mfma_f32_32x32x16_bf16 v[66:81], v[208:211], v[106:109], v[66:81]
	s_waitcnt lgkmcnt(2)
	v_mfma_f32_32x32x16_bf16 v[82:97], v[238:241], v[102:105], v[82:97]
	v_mfma_f32_32x32x16_bf16 v[66:81], v[242:245], v[102:105], v[66:81]
	s_waitcnt lgkmcnt(0)
	v_mfma_f32_32x32x16_bf16 v[82:97], v[246:249], v[98:101], v[82:97]
	v_mfma_f32_32x32x16_bf16 v[66:81], v[250:253], v[98:101], v[66:81]
	s_add_i32 m0, s73, 0x14000
	s_nop 0
	global_load_lds_dwordx4 v[134:135], off
	s_add_i32 m0, s73, 0x16000
	s_nop 0
	global_load_lds_dwordx4 v[200:201], off
	ds_read_b64_tr_b16 v[136:137], v173 offset:32768
	ds_read_b64_tr_b16 v[138:139], v174 offset:32768
	ds_read_b64_tr_b16 v[140:141], v170 offset:32768
	ds_read_b64_tr_b16 v[142:143], v172 offset:32768
	ds_read_b64_tr_b16 v[204:205], v168 offset:32768
	ds_read_b64_tr_b16 v[206:207], v171 offset:32768
	ds_read_b64_tr_b16 v[208:209], v145 offset:32768
	ds_read_b64_tr_b16 v[210:211], v169 offset:32768
	ds_read_b64_tr_b16 v[238:239], v173 offset:36864
	ds_read_b64_tr_b16 v[240:241], v174 offset:36864
	ds_read_b64_tr_b16 v[242:243], v170 offset:36864
	ds_read_b64_tr_b16 v[244:245], v172 offset:36864
	v_max3_f32 v122, v82, v66, v83
	v_max3_f32 v123, v67, v84, v68
	v_max3_f32 v124, v85, v69, v86
	v_max3_f32 v125, v70, v87, v71
	v_max3_f32 v122, v122, v88, v72
	v_max3_f32 v123, v123, v89, v73
	v_max3_f32 v124, v124, v90, v74
	v_max3_f32 v125, v125, v91, v75
	v_max3_f32 v122, v122, v92, v76
	v_max3_f32 v123, v123, v93, v77
	v_max3_f32 v124, v124, v94, v78
	v_max3_f32 v125, v125, v95, v79
	v_max3_f32 v122, v122, v96, v80
	v_max3_f32 v123, v123, v97, v81
	v_max3_f32 v122, v122, v123, v124
	v_max_f32_e32 v122, v122, v125
	v_mov_b32_e32 v203, v122
	s_nop 1
	v_permlane32_swap_b32_e32 v122, v203
	s_nop 1
	v_max_f32_e32 v122, v122, v203
	s_mov_b32 s70, 0
	v_cmp_lt_f32_e32 vcc, 0x41000000, v122
	s_cmp_eq_u32 s71, 0
	s_cbranch_scc1 .Lat1_u0_first
	s_cbranch_vccz .Lat1_u0_norescale
	s_branch .Lat1_u0_rescale

; #define LAS __attribute__((address_space(3)))
; __device__ __forceinline__ unsigned pk2(float lo, float hi) { f32x2 v = {lo, hi}; bf16x2_t b = __builtin_convertvector(v, bf16x2_t); return __builtin_bit_cast(unsigned, b); }
; __device__ __forceinline__ s16x4 vtr(LAS const unsigned char* p) { return __builtin_bit_cast(s16x4, __builtin_amdgcn_ds_read_tr16_b64_v4i16((LAS v4i16_t*)p)); }
; __device__ __forceinline__ bf16x8 cat8(s16x4 a, s16x4 b) { return (bf16x8){a[0], a[1], a[2], a[3], b[0], b[1], b[2], b[3]}; }
; __device__ __forceinline__ void attn_block(LAS unsigned char* lds, const bf16_t* P, bf16_t* mix, int b, int h, int qb, float lam, float outscale, const float* subln) {
;     ...
;             for (int ks = 0; ks < 4; ++ks) { ka[ks][0] = *(const LAS bf16x8*)(Kb + kbase[ks]); ka[ks][1] = *(const LAS bf16x8*)(Kb + kbase[ks] + 8192); }
;     ...
; #pragma unroll
;             for (int j = 0; j < 16; ++j) { s0[j] = __builtin_amdgcn_exp2f(s0[j] - mrun); s1[j] = __builtin_amdgcn_exp2f(s1[j] - mrun); }
;             float ps0 = 0.f, ps1 = 0.f, ps2 = 0.f, ps3 = 0.f;
; #pragma unroll
;             for (int j = 0; j < 16; j += 2) { ps0 += s0[j]; ps1 += s1[j]; ps2 += s0[j + 1]; ps3 += s1[j + 1]; }
;             lrun += (ps0 + ps1) + (ps2 + ps3);
;             bf16x8 pb[4];
; #pragma unroll
;             for (int s2 = 0; s2 < 2; ++s2) {
;                 u32x4 w0, w1;
;                 w0.x = pk2(s0[8 * s2 + 0], s0[8 * s2 + 1]); w0.y = pk2(s0[8 * s2 + 2], s0[8 * s2 + 3]); w0.z = pk2(s0[8 * s2 + 4], s0[8 * s2 + 5]); w0.w = pk2(s0[8 * s2 + 6], s0[8 * s2 + 7]);
;                 w1.x = pk2(s1[8 * s2 + 0], s1[8 * s2 + 1]); w1.y = pk2(s1[8 * s2 + 2], s1[8 * s2 + 3]); w1.z = pk2(s1[8 * s2 + 4], s1[8 * s2 + 5]); w1.w = pk2(s1[8 * s2 + 6], s1[8 * s2 + 7]);
;                 pb[s2] = __builtin_bit_cast(bf16x8, w0); pb[2 + s2] = __builtin_bit_cast(bf16x8, w1);
;             }
; #pragma unroll
;             for (int s = 0; s < 4; ++s) {
; #pragma unroll
;                 for (int c = 0; c < 4; ++c) {
;                     const s16x4 v0 = vtr(Vb + vbase[c][0] + 4096 * s);
;                     const s16x4 v1 = vtr(Vb + vbase[c][1] + 4096 * s);
;                     o[c] = __builtin_amdgcn_mfma_f32_32x32x16_bf16(cat8(v0, v1), pb[s], o[c], 0, 0, 0);
;                 }
;             }
.Lat1_u0_norescale:
	v_exp_f32_e32 v82, v82
	v_exp_f32_e32 v83, v83
	v_exp_f32_e32 v84, v84
	v_exp_f32_e32 v85, v85
	v_exp_f32_e32 v86, v86
	v_exp_f32_e32 v87, v87
	v_exp_f32_e32 v88, v88
	v_exp_f32_e32 v89, v89
	v_exp_f32_e32 v90, v90
	v_exp_f32_e32 v91, v91
	v_exp_f32_e32 v92, v92
	v_exp_f32_e32 v93, v93
	v_exp_f32_e32 v94, v94
	v_exp_f32_e32 v95, v95
	v_exp_f32_e32 v96, v96
	v_exp_f32_e32 v97, v97
	v_cvt_pk_bf16_f32 v184, v82, v83
	v_cvt_pk_bf16_f32 v185, v84, v85
	v_cvt_pk_bf16_f32 v186, v86, v87
	v_cvt_pk_bf16_f32 v187, v88, v89
	v_cvt_pk_bf16_f32 v188, v90, v91
	v_cvt_pk_bf16_f32 v189, v92, v93
	v_cvt_pk_bf16_f32 v190, v94, v95
	v_cvt_pk_bf16_f32 v191, v96, v97
	v_add_f32_e32 v122, v82, v83
	v_add_f32_e32 v123, v84, v85
	v_add_f32_e32 v122, v122, v86
	v_add_f32_e32 v123, v123, v87
	v_add_f32_e32 v122, v122, v88
	v_add_f32_e32 v123, v123, v89
	v_add_f32_e32 v122, v122, v123
	v_add_f32_e32 v167, v167, v122
	v_add_f32_e32 v124, v90, v91
	v_add_f32_e32 v125, v92, v93
	v_add_f32_e32 v124, v124, v94
	v_add_f32_e32 v125, v125, v95
	v_add_f32_e32 v124, v124, v96
	v_add_f32_e32 v125, v125, v97
	v_add_f32_e32 v124, v124, v125
	v_add_f32_e32 v167, v167, v124
	s_waitcnt lgkmcnt(8)
	v_mfma_f32_32x32x16_bf16 v[50:65], v[136:139], v[184:187], v[50:65]
	ds_read_b64_tr_b16 v[246:247], v168 offset:36864
	ds_read_b64_tr_b16 v[248:249], v171 offset:36864
	v_exp_f32_e32 v66, v66
	v_exp_f32_e32 v67, v67
	v_exp_f32_e32 v68, v68
	v_mfma_f32_32x32x16_bf16 v[34:49], v[140:143], v[184:187], v[34:49]
	ds_read_b64_tr_b16 v[250:251], v145 offset:36864
	ds_read_b64_tr_b16 v[252:253], v169 offset:36864
	v_exp_f32_e32 v69, v69
	v_exp_f32_e32 v70, v70
	v_exp_f32_e32 v71, v71
	s_add_i32 m0, s73, 0x1b800
	s_nop 0
	global_load_lds_dwordx4 v[134:135], off offset:2048
	s_waitcnt lgkmcnt(8)
	v_mfma_f32_32x32x16_bf16 v[18:33], v[204:207], v[184:187], v[18:33]
	ds_read_b64_tr_b16 v[136:137], v173 offset:40960
	ds_read_b64_tr_b16 v[138:139], v174 offset:40960
	v_exp_f32_e32 v72, v72
	v_exp_f32_e32 v73, v73
	v_cvt_pk_bf16_f32 v192, v66, v67
	v_mfma_f32_32x32x16_bf16 v[2:17], v[208:211], v[184:187], v[2:17]
	ds_read_b64_tr_b16 v[140:141], v170 offset:40960
	ds_read_b64_tr_b16 v[142:143], v172 offset:40960
	v_cvt_pk_bf16_f32 v193, v68, v69
	v_cvt_pk_bf16_f32 v194, v70, v71
	v_cvt_pk_bf16_f32 v195, v72, v73
	s_add_i32 m0, s73, 0x1d800
	s_nop 0
	global_load_lds_dwordx4 v[200:201], off offset:2048
	v_lshl_add_u64 v[134:135], v[134:135], 0, s[40:41]
	v_lshl_add_u64 v[200:201], v[200:201], 0, s[40:41]
	s_waitcnt lgkmcnt(8)
	v_mfma_f32_32x32x16_bf16 v[50:65], v[238:241], v[188:191], v[50:65]
	ds_read_b64_tr_b16 v[204:205], v168 offset:40960
	ds_read_b64_tr_b16 v[206:207], v171 offset:40960
	v_exp_f32_e32 v74, v74
	v_exp_f32_e32 v75, v75
	v_exp_f32_e32 v76, v76
	v_mfma_f32_32x32x16_bf16 v[34:49], v[242:245], v[188:191], v[34:49]
	ds_read_b64_tr_b16 v[208:209], v145 offset:40960
	ds_read_b64_tr_b16 v[210:211], v169 offset:40960
	v_exp_f32_e32 v77, v77
	v_exp_f32_e32 v78, v78
	v_exp_f32_e32 v79, v79
	s_waitcnt lgkmcnt(8)
	v_mfma_f32_32x32x16_bf16 v[18:33], v[246:249], v[188:191], v[18:33]
	ds_read_b64_tr_b16 v[238:239], v173 offset:45056
	ds_read_b64_tr_b16 v[240:241], v174 offset:45056
	v_exp_f32_e32 v80, v80
	v_exp_f32_e32 v81, v81
	v_cvt_pk_bf16_f32 v196, v74, v75
	v_mfma_f32_32x32x16_bf16 v[2:17], v[250:253], v[188:191], v[2:17]
	ds_read_b64_tr_b16 v[242:243], v170 offset:45056
	ds_read_b64_tr_b16 v[244:245], v172 offset:45056
	v_cvt_pk_bf16_f32 v197, v76, v77
	v_cvt_pk_bf16_f32 v198, v78, v79
	v_cvt_pk_bf16_f32 v199, v80, v81
	s_waitcnt lgkmcnt(8)
	v_mfma_f32_32x32x16_bf16 v[50:65], v[136:139], v[192:195], v[50:65]
	ds_read_b64_tr_b16 v[246:247], v168 offset:45056
	ds_read_b64_tr_b16 v[248:249], v171 offset:45056
	v_add_f32_e32 v0, v66, v67
	v_add_f32_e32 v203, v68, v69
	v_add_f32_e32 v0, v0, v70
	v_mfma_f32_32x32x16_bf16 v[34:49], v[140:143], v[192:195], v[34:49]
	ds_read_b64_tr_b16 v[250:251], v145 offset:45056
	ds_read_b64_tr_b16 v[252:253], v169 offset:45056
	v_add_f32_e32 v203, v203, v71
	v_add_f32_e32 v0, v0, v72
	v_add_f32_e32 v203, v203, v73
	s_waitcnt lgkmcnt(8)
	v_mfma_f32_32x32x16_bf16 v[18:33], v[204:207], v[192:195], v[18:33]
	v_add_f32_e32 v0, v0, v203
	v_add_f32_e32 v167, v167, v0
	v_add_f32_e32 v0, v74, v75
	ds_read_b128 v[136:139], v180 offset:16384
	ds_read_b128 v[140:143], v180 offset:24576
	v_mfma_f32_32x32x16_bf16 v[2:17], v[208:211], v[192:195], v[2:17]
	v_add_f32_e32 v203, v76, v77
	v_add_f32_e32 v0, v0, v78
	v_add_f32_e32 v203, v203, v79
	ds_read_b128 v[204:207], v181 offset:16384
	ds_read_b128 v[208:211], v181 offset:24576
	s_waitcnt lgkmcnt(8)
	v_mfma_f32_32x32x16_bf16 v[50:65], v[238:241], v[196:199], v[50:65]
	v_add_f32_e32 v0, v0, v80
	v_add_f32_e32 v203, v203, v81
	v_add_f32_e32 v0, v0, v203
	v_mfma_f32_32x32x16_bf16 v[34:49], v[242:245], v[196:199], v[34:49]
	v_add_f32_e32 v167, v167, v0
	ds_read_b128 v[238:241], v178 offset:16384
	ds_read_b128 v[242:245], v178 offset:24576
	s_waitcnt lgkmcnt(6)
	v_mfma_f32_32x32x16_bf16 v[18:33], v[246:249], v[196:199], v[18:33]
	v_mfma_f32_32x32x16_bf16 v[2:17], v[250:253], v[196:199], v[2:17]
	ds_read_b128 v[246:249], v177 offset:16384
	ds_read_b128 v[250:253], v177 offset:24576
	s_waitcnt vmcnt(6)
	s_add_i32 s71, s71, 64
	s_barrier
; #define LAS __attribute__((address_space(3)))
; __device__ __forceinline__ float max3f(float a, float b, float c) { float r; asm("v_max3_f32 %0, %1, %2, %3" : "=v"(r) : "v"(a), "v"(b), "v"(c)); return r; }
; __device__ __forceinline__ void attn_block(LAS unsigned char* lds, const bf16_t* P, bf16_t* mix, int b, int h, int qb, float lam, float outscale, const float* subln) {
;     ...
;         const int kb = 64 * kt;
;         if (kb <= qw0 + 31) {
;             LAS const unsigned char* Kb = lds + ATT_K0 + buf * 16384;
;             LAS const unsigned char* Vb = lds + ATT_V0 + buf * 16384;
;             f32x16 s0, s1;
; #pragma unroll
;             for (int j = 0; j < 16; ++j) { s0[j] = 0.f; s1[j] = 0.f; }
;             bf16x8 ka[4][2];
; #pragma unroll
;             for (int ks = 0; ks < 4; ++ks) { ka[ks][0] = *(const LAS bf16x8*)(Kb + kbase[ks]); ka[ks][1] = *(const LAS bf16x8*)(Kb + kbase[ks] + 8192); }
;             __builtin_amdgcn_sched_barrier(0);
; #pragma unroll
;             for (int ks = 0; ks < 4; ++ks) {
;                 s0 = __builtin_amdgcn_mfma_f32_32x32x16_bf16(ka[ks][0], qf[ks], s0, 0, 0, 0);
;                 s1 = __builtin_amdgcn_mfma_f32_32x32x16_bf16(ka[ks][1], qf[ks], s1, 0, 0, 0);
;             }
;             if (kb + 63 > qw0) {
; #pragma unroll
;                 for (int j = 0; j < 16; ++j) { const int key = kb + crow(j, hi); if (key > qrow) s0[j] = -INFINITY; if (key + 32 > qrow) s1[j] = -INFINITY; }
;             }
;             float mxa = max3f(s0[0], s1[0], s0[1]), mxb = max3f(s1[1], s0[2], s1[2]), mxc = max3f(s0[3], s1[3], s0[4]), mxd = max3f(s1[4], s0[5], s1[5]);
;             mxa = max3f(mxa, s0[6], s1[6]); mxb = max3f(mxb, s0[7], s1[7]); mxc = max3f(mxc, s0[8], s1[8]); mxd = max3f(mxd, s0[9], s1[9]);
;             mxa = max3f(mxa, s0[10], s1[10]); mxb = max3f(mxb, s0[11], s1[11]); mxc = max3f(mxc, s0[12], s1[12]); mxd = max3f(mxd, s0[13], s1[13]);
;             mxa = max3f(mxa, s0[14], s1[14]); mxb = max3f(mxb, s0[15], s1[15]);
;             float mx = max3f(mxa, mxb, max3f(mxc, mxd, mxd));
;             { auto rr = __builtin_amdgcn_permlane32_swap(__builtin_bit_cast(unsigned, mx), __builtin_bit_cast(unsigned, mx), false, false);
;               mx = fmaxf(__builtin_bit_cast(float, rr[0]), __builtin_bit_cast(float, rr[1])); }
;             if (__any(mx > mrun + 8.0f)) {
	s_waitcnt lgkmcnt(6)
	v_mfma_f32_32x32x16_bf16 v[82:97], v[136:139], v[110:113], v[222:237]
	v_mfma_f32_32x32x16_bf16 v[66:81], v[140:143], v[110:113], v[222:237]
	s_waitcnt lgkmcnt(4)
	v_mfma_f32_32x32x16_bf16 v[82:97], v[204:207], v[106:109], v[82:97]
	v_mfma_f32_32x32x16_bf16 v[66:81], v[208:211], v[106:109], v[66:81]
	s_waitcnt lgkmcnt(2)
	v_mfma_f32_32x32x16_bf16 v[82:97], v[238:241], v[102:105], v[82:97]
	v_mfma_f32_32x32x16_bf16 v[66:81], v[242:245], v[102:105], v[66:81]
	s_waitcnt lgkmcnt(0)
	v_mfma_f32_32x32x16_bf16 v[82:97], v[246:249], v[98:101], v[82:97]
	v_mfma_f32_32x32x16_bf16 v[66:81], v[250:253], v[98:101], v[66:81]
	s_add_i32 m0, s73, 0x0
	s_nop 0
	global_load_lds_dwordx4 v[134:135], off
	s_add_i32 m0, s73, 0x2000
	s_nop 0
	global_load_lds_dwordx4 v[200:201], off
	ds_read_b64_tr_b16 v[136:137], v173 offset:49152
	ds_read_b64_tr_b16 v[138:139], v174 offset:49152
	ds_read_b64_tr_b16 v[140:141], v170 offset:49152
	ds_read_b64_tr_b16 v[142:143], v172 offset:49152
	ds_read_b64_tr_b16 v[204:205], v168 offset:49152
	ds_read_b64_tr_b16 v[206:207], v171 offset:49152
	ds_read_b64_tr_b16 v[208:209], v145 offset:49152
	ds_read_b64_tr_b16 v[210:211], v169 offset:49152
	ds_read_b64_tr_b16 v[238:239], v173 offset:53248
	ds_read_b64_tr_b16 v[240:241], v174 offset:53248
	ds_read_b64_tr_b16 v[242:243], v170 offset:53248
	ds_read_b64_tr_b16 v[244:245], v172 offset:53248
	v_max3_f32 v122, v82, v66, v83
	v_max3_f32 v123, v67, v84, v68
	v_max3_f32 v124, v85, v69, v86
	v_max3_f32 v125, v70, v87, v71
	v_max3_f32 v122, v122, v88, v72
	v_max3_f32 v123, v123, v89, v73
	v_max3_f32 v124, v124, v90, v74
	v_max3_f32 v125, v125, v91, v75
	v_max3_f32 v122, v122, v92, v76
	v_max3_f32 v123, v123, v93, v77
	v_max3_f32 v124, v124, v94, v78
	v_max3_f32 v125, v125, v95, v79
	v_max3_f32 v122, v122, v96, v80
	v_max3_f32 v123, v123, v97, v81
	v_max3_f32 v122, v122, v123, v124
	v_max_f32_e32 v122, v122, v125
	v_mov_b32_e32 v203, v122
	s_nop 1
	v_permlane32_swap_b32_e32 v122, v203
	s_nop 1
	v_max_f32_e32 v122, v122, v203
	s_mov_b32 s70, 0
	v_cmp_lt_f32_e32 vcc, 0x41000000, v122
	s_cmp_eq_u32 s71, 0
	s_cbranch_scc1 .Lat1_u1_first
	s_cbranch_vccz .Lat1_u1_norescale
	s_branch .Lat1_u1_rescale

; #define LAS __attribute__((address_space(3)))
; __device__ __forceinline__ unsigned pk2(float lo, float hi) { f32x2 v = {lo, hi}; bf16x2_t b = __builtin_convertvector(v, bf16x2_t); return __builtin_bit_cast(unsigned, b); }
; __device__ __forceinline__ s16x4 vtr(LAS const unsigned char* p) { return __builtin_bit_cast(s16x4, __builtin_amdgcn_ds_read_tr16_b64_v4i16((LAS v4i16_t*)p)); }
; __device__ __forceinline__ bf16x8 cat8(s16x4 a, s16x4 b) { return (bf16x8){a[0], a[1], a[2], a[3], b[0], b[1], b[2], b[3]}; }
; __device__ __forceinline__ void attn_block(LAS unsigned char* lds, const bf16_t* P, bf16_t* mix, int b, int h, int qb, float lam, float outscale, const float* subln) {
;     ...
;             for (int ks = 0; ks < 4; ++ks) { ka[ks][0] = *(const LAS bf16x8*)(Kb + kbase[ks]); ka[ks][1] = *(const LAS bf16x8*)(Kb + kbase[ks] + 8192); }
;     ...
; #pragma unroll
;             for (int j = 0; j < 16; ++j) { s0[j] = __builtin_amdgcn_exp2f(s0[j] - mrun); s1[j] = __builtin_amdgcn_exp2f(s1[j] - mrun); }
;             float ps0 = 0.f, ps1 = 0.f, ps2 = 0.f, ps3 = 0.f;
; #pragma unroll
;             for (int j = 0; j < 16; j += 2) { ps0 += s0[j]; ps1 += s1[j]; ps2 += s0[j + 1]; ps3 += s1[j + 1]; }
;             lrun += (ps0 + ps1) + (ps2 + ps3);
;             bf16x8 pb[4];
; #pragma unroll
;             for (int s2 = 0; s2 < 2; ++s2) {
;                 u32x4 w0, w1;
;                 w0.x = pk2(s0[8 * s2 + 0], s0[8 * s2 + 1]); w0.y = pk2(s0[8 * s2 + 2], s0[8 * s2 + 3]); w0.z = pk2(s0[8 * s2 + 4], s0[8 * s2 + 5]); w0.w = pk2(s0[8 * s2 + 6], s0[8 * s2 + 7]);
;                 w1.x = pk2(s1[8 * s2 + 0], s1[8 * s2 + 1]); w1.y = pk2(s1[8 * s2 + 2], s1[8 * s2 + 3]); w1.z = pk2(s1[8 * s2 + 4], s1[8 * s2 + 5]); w1.w = pk2(s1[8 * s2 + 6], s1[8 * s2 + 7]);
;                 pb[s2] = __builtin_bit_cast(bf16x8, w0); pb[2 + s2] = __builtin_bit_cast(bf16x8, w1);
;             }
; #pragma unroll
;             for (int s = 0; s < 4; ++s) {
; #pragma unroll
;                 for (int c = 0; c < 4; ++c) {
;                     const s16x4 v0 = vtr(Vb + vbase[c][0] + 4096 * s);
;                     const s16x4 v1 = vtr(Vb + vbase[c][1] + 4096 * s);
;                     o[c] = __builtin_amdgcn_mfma_f32_32x32x16_bf16(cat8(v0, v1), pb[s], o[c], 0, 0, 0);
;                 }
;             }
.Lat1_u1_norescale:
	v_exp_f32_e32 v82, v82
	v_exp_f32_e32 v83, v83
	v_exp_f32_e32 v84, v84
	v_exp_f32_e32 v85, v85
	v_exp_f32_e32 v86, v86
	v_exp_f32_e32 v87, v87
	v_exp_f32_e32 v88, v88
	v_exp_f32_e32 v89, v89
	v_exp_f32_e32 v90, v90
	v_exp_f32_e32 v91, v91
	v_exp_f32_e32 v92, v92
	v_exp_f32_e32 v93, v93
	v_exp_f32_e32 v94, v94
	v_exp_f32_e32 v95, v95
	v_exp_f32_e32 v96, v96
	v_exp_f32_e32 v97, v97
	v_cvt_pk_bf16_f32 v184, v82, v83
	v_cvt_pk_bf16_f32 v185, v84, v85
	v_cvt_pk_bf16_f32 v186, v86, v87
	v_cvt_pk_bf16_f32 v187, v88, v89
	v_cvt_pk_bf16_f32 v188, v90, v91
	v_cvt_pk_bf16_f32 v189, v92, v93
	v_cvt_pk_bf16_f32 v190, v94, v95
	v_cvt_pk_bf16_f32 v191, v96, v97
	v_add_f32_e32 v122, v82, v83
	v_add_f32_e32 v123, v84, v85
	v_add_f32_e32 v122, v122, v86
	v_add_f32_e32 v123, v123, v87
	v_add_f32_e32 v122, v122, v88
	v_add_f32_e32 v123, v123, v89
	v_add_f32_e32 v122, v122, v123
	v_add_f32_e32 v167, v167, v122
	v_add_f32_e32 v124, v90, v91
	v_add_f32_e32 v125, v92, v93
	v_add_f32_e32 v124, v124, v94
	v_add_f32_e32 v125, v125, v95
	v_add_f32_e32 v124, v124, v96
	v_add_f32_e32 v125, v125, v97
	v_add_f32_e32 v124, v124, v125
	v_add_f32_e32 v167, v167, v124
	s_waitcnt lgkmcnt(8)
	v_mfma_f32_32x32x16_bf16 v[50:65], v[136:139], v[184:187], v[50:65]
	ds_read_b64_tr_b16 v[246:247], v168 offset:53248
	ds_read_b64_tr_b16 v[248:249], v171 offset:53248
	v_exp_f32_e32 v66, v66
	v_exp_f32_e32 v67, v67
	v_exp_f32_e32 v68, v68
	v_mfma_f32_32x32x16_bf16 v[34:49], v[140:143], v[184:187], v[34:49]
	ds_read_b64_tr_b16 v[250:251], v145 offset:53248
	ds_read_b64_tr_b16 v[252:253], v169 offset:53248
	v_exp_f32_e32 v69, v69
	v_exp_f32_e32 v70, v70
	v_exp_f32_e32 v71, v71
	s_add_i32 m0, s73, 0x7800
	s_nop 0
	global_load_lds_dwordx4 v[134:135], off offset:2048
	s_waitcnt lgkmcnt(8)
	v_mfma_f32_32x32x16_bf16 v[18:33], v[204:207], v[184:187], v[18:33]
	ds_read_b64_tr_b16 v[136:137], v173 offset:57344
	ds_read_b64_tr_b16 v[138:139], v174 offset:57344
	v_exp_f32_e32 v72, v72
	v_exp_f32_e32 v73, v73
	v_cvt_pk_bf16_f32 v192, v66, v67
	v_mfma_f32_32x32x16_bf16 v[2:17], v[208:211], v[184:187], v[2:17]
	ds_read_b64_tr_b16 v[140:141], v170 offset:57344
	ds_read_b64_tr_b16 v[142:143], v172 offset:57344
	v_cvt_pk_bf16_f32 v193, v68, v69
	v_cvt_pk_bf16_f32 v194, v70, v71
	v_cvt_pk_bf16_f32 v195, v72, v73
	s_add_i32 m0, s73, 0x9800
	s_nop 0
	global_load_lds_dwordx4 v[200:201], off offset:2048
	v_lshl_add_u64 v[134:135], v[134:135], 0, s[40:41]
	v_lshl_add_u64 v[200:201], v[200:201], 0, s[40:41]
	s_waitcnt lgkmcnt(8)
	v_mfma_f32_32x32x16_bf16 v[50:65], v[238:241], v[188:191], v[50:65]
	ds_read_b64_tr_b16 v[204:205], v168 offset:57344
	ds_read_b64_tr_b16 v[206:207], v171 offset:57344
	v_exp_f32_e32 v74, v74
	v_exp_f32_e32 v75, v75
	v_exp_f32_e32 v76, v76
	v_mfma_f32_32x32x16_bf16 v[34:49], v[242:245], v[188:191], v[34:49]
	ds_read_b64_tr_b16 v[208:209], v145 offset:57344
	ds_read_b64_tr_b16 v[210:211], v169 offset:57344
	v_exp_f32_e32 v77, v77
	v_exp_f32_e32 v78, v78
	v_exp_f32_e32 v79, v79
	s_waitcnt lgkmcnt(8)
	v_mfma_f32_32x32x16_bf16 v[18:33], v[246:249], v[188:191], v[18:33]
	ds_read_b64_tr_b16 v[238:239], v173 offset:61440
	ds_read_b64_tr_b16 v[240:241], v174 offset:61440
	v_exp_f32_e32 v80, v80
	v_exp_f32_e32 v81, v81
	v_cvt_pk_bf16_f32 v196, v74, v75
	v_mfma_f32_32x32x16_bf16 v[2:17], v[250:253], v[188:191], v[2:17]
	ds_read_b64_tr_b16 v[242:243], v170 offset:61440
	ds_read_b64_tr_b16 v[244:245], v172 offset:61440
	v_cvt_pk_bf16_f32 v197, v76, v77
	v_cvt_pk_bf16_f32 v198, v78, v79
	v_cvt_pk_bf16_f32 v199, v80, v81
	s_waitcnt lgkmcnt(8)
	v_mfma_f32_32x32x16_bf16 v[50:65], v[136:139], v[192:195], v[50:65]
	ds_read_b64_tr_b16 v[246:247], v168 offset:61440
	ds_read_b64_tr_b16 v[248:249], v171 offset:61440
	v_add_f32_e32 v0, v66, v67
	v_add_f32_e32 v203, v68, v69
	v_add_f32_e32 v0, v0, v70
	v_mfma_f32_32x32x16_bf16 v[34:49], v[140:143], v[192:195], v[34:49]
	ds_read_b64_tr_b16 v[250:251], v145 offset:61440
	ds_read_b64_tr_b16 v[252:253], v169 offset:61440
	v_add_f32_e32 v203, v203, v71
	v_add_f32_e32 v0, v0, v72
	v_add_f32_e32 v203, v203, v73
	s_waitcnt lgkmcnt(8)
	v_mfma_f32_32x32x16_bf16 v[18:33], v[204:207], v[192:195], v[18:33]
	v_add_f32_e32 v0, v0, v203
	v_add_f32_e32 v167, v167, v0
	v_add_f32_e32 v0, v74, v75
	ds_read_b128 v[136:139], v126 offset:0
	ds_read_b128 v[140:143], v126 offset:8192
	v_mfma_f32_32x32x16_bf16 v[2:17], v[208:211], v[192:195], v[2:17]
	v_add_f32_e32 v203, v76, v77
	v_add_f32_e32 v0, v0, v78
	v_add_f32_e32 v203, v203, v79
	ds_read_b128 v[204:207], v127 offset:0
	ds_read_b128 v[208:211], v127 offset:8192
	s_waitcnt lgkmcnt(8)
	v_mfma_f32_32x32x16_bf16 v[50:65], v[238:241], v[196:199], v[50:65]
	v_add_f32_e32 v0, v0, v80
	v_add_f32_e32 v203, v203, v81
	v_add_f32_e32 v0, v0, v203
	v_mfma_f32_32x32x16_bf16 v[34:49], v[242:245], v[196:199], v[34:49]
	v_add_f32_e32 v167, v167, v0
	ds_read_b128 v[238:241], v128 offset:0
	ds_read_b128 v[242:245], v128 offset:8192
	s_waitcnt lgkmcnt(6)
	v_mfma_f32_32x32x16_bf16 v[18:33], v[246:249], v[196:199], v[18:33]
	v_mfma_f32_32x32x16_bf16 v[2:17], v[250:253], v[196:199], v[2:17]
	ds_read_b128 v[246:249], v129 offset:0
	ds_read_b128 v[250:253], v129 offset:8192
	s_waitcnt vmcnt(6)
	s_add_i32 s71, s71, 64
	s_barrier
; #define LAS __attribute__((address_space(3)))
; __device__ __forceinline__ float max3f(float a, float b, float c) { float r; asm("v_max3_f32 %0, %1, %2, %3" : "=v"(r) : "v"(a), "v"(b), "v"(c)); return r; }
; __device__ __forceinline__ void attn_block(LAS unsigned char* lds, const bf16_t* P, bf16_t* mix, int b, int h, int qb, float lam, float outscale, const float* subln) {
;     ...
;         const int kb = 64 * kt;
;         if (kb <= qw0 + 31) {
;             LAS const unsigned char* Kb = lds + ATT_K0 + buf * 16384;
;             LAS const unsigned char* Vb = lds + ATT_V0 + buf * 16384;
;             f32x16 s0, s1;
; #pragma unroll
;             for (int j = 0; j < 16; ++j) { s0[j] = 0.f; s1[j] = 0.f; }
;             bf16x8 ka[4][2];
; #pragma unroll
;             for (int ks = 0; ks < 4; ++ks) { ka[ks][0] = *(const LAS bf16x8*)(Kb + kbase[ks]); ka[ks][1] = *(const LAS bf16x8*)(Kb + kbase[ks] + 8192); }
;             __builtin_amdgcn_sched_barrier(0);
; #pragma unroll
;             for (int ks = 0; ks < 4; ++ks) {
;                 s0 = __builtin_amdgcn_mfma_f32_32x32x16_bf16(ka[ks][0], qf[ks], s0, 0, 0, 0);
;                 s1 = __builtin_amdgcn_mfma_f32_32x32x16_bf16(ka[ks][1], qf[ks], s1, 0, 0, 0);
;             }
;             if (kb + 63 > qw0) {
; #pragma unroll
;                 for (int j = 0; j < 16; ++j) { const int key = kb + crow(j, hi); if (key > qrow) s0[j] = -INFINITY; if (key + 32 > qrow) s1[j] = -INFINITY; }
;             }
;             float mxa = max3f(s0[0], s1[0], s0[1]), mxb = max3f(s1[1], s0[2], s1[2]), mxc = max3f(s0[3], s1[3], s0[4]), mxd = max3f(s1[4], s0[5], s1[5]);
;             mxa = max3f(mxa, s0[6], s1[6]); mxb = max3f(mxb, s0[7], s1[7]); mxc = max3f(mxc, s0[8], s1[8]); mxd = max3f(mxd, s0[9], s1[9]);
;             mxa = max3f(mxa, s0[10], s1[10]); mxb = max3f(mxb, s0[11], s1[11]); mxc = max3f(mxc, s0[12], s1[12]); mxd = max3f(mxd, s0[13], s1[13]);
;             mxa = max3f(mxa, s0[14], s1[14]); mxb = max3f(mxb, s0[15], s1[15]);
;             float mx = max3f(mxa, mxb, max3f(mxc, mxd, mxd));
;             { auto rr = __builtin_amdgcn_permlane32_swap(__builtin_bit_cast(unsigned, mx), __builtin_bit_cast(unsigned, mx), false, false);
;               mx = fmaxf(__builtin_bit_cast(float, rr[0]), __builtin_bit_cast(float, rr[1])); }
;             if (__any(mx > mrun + 8.0f)) {
	s_waitcnt lgkmcnt(6)
	v_mfma_f32_32x32x16_bf16 v[82:97], v[136:139], v[110:113], v[222:237]
	v_mfma_f32_32x32x16_bf16 v[66:81], v[140:143], v[110:113], v[222:237]
	s_waitcnt lgkmcnt(4)
	v_mfma_f32_32x32x16_bf16 v[82:97], v[204:207], v[106:109], v[82:97]
	v_mfma_f32_32x32x16_bf16 v[66:81], v[208:211], v[106:109], v[66:81]
	s_waitcnt lgkmcnt(2)
	v_mfma_f32_32x32x16_bf16 v[82:97], v[238:241], v[102:105], v[82:97]
	v_mfma_f32_32x32x16_bf16 v[66:81], v[242:245], v[102:105], v[66:81]
	s_waitcnt lgkmcnt(0)
	v_mfma_f32_32x32x16_bf16 v[82:97], v[246:249], v[98:101], v[82:97]
	v_mfma_f32_32x32x16_bf16 v[66:81], v[250:253], v[98:101], v[66:81]
	s_add_i32 m0, s73, 0x4000
	s_nop 0
	global_load_lds_dwordx4 v[134:135], off
	s_add_i32 m0, s73, 0x6000
	s_nop 0
	global_load_lds_dwordx4 v[200:201], off
	ds_read_b64_tr_b16 v[136:137], v114 offset:32768
	ds_read_b64_tr_b16 v[138:139], v115 offset:32768
	ds_read_b64_tr_b16 v[140:141], v116 offset:32768
	ds_read_b64_tr_b16 v[142:143], v117 offset:32768
	ds_read_b64_tr_b16 v[204:205], v118 offset:32768
	ds_read_b64_tr_b16 v[206:207], v119 offset:32768
	ds_read_b64_tr_b16 v[208:209], v120 offset:32768
	ds_read_b64_tr_b16 v[210:211], v121 offset:32768
	ds_read_b64_tr_b16 v[238:239], v114 offset:36864
	ds_read_b64_tr_b16 v[240:241], v115 offset:36864
	ds_read_b64_tr_b16 v[242:243], v116 offset:36864
	ds_read_b64_tr_b16 v[244:245], v117 offset:36864
	v_max3_f32 v122, v82, v66, v83
	v_max3_f32 v123, v67, v84, v68
	v_max3_f32 v124, v85, v69, v86
	v_max3_f32 v125, v70, v87, v71
	v_max3_f32 v122, v122, v88, v72
	v_max3_f32 v123, v123, v89, v73
	v_max3_f32 v124, v124, v90, v74
	v_max3_f32 v125, v125, v91, v75
	v_max3_f32 v122, v122, v92, v76
	v_max3_f32 v123, v123, v93, v77
	v_max3_f32 v124, v124, v94, v78
	v_max3_f32 v125, v125, v95, v79
	v_max3_f32 v122, v122, v96, v80
	v_max3_f32 v123, v123, v97, v81
	v_max3_f32 v122, v122, v123, v124
	v_max_f32_e32 v122, v122, v125
	v_mov_b32_e32 v203, v122
	s_nop 1
	v_permlane32_swap_b32_e32 v122, v203
	s_nop 1
	v_max_f32_e32 v122, v122, v203
	s_mov_b32 s70, 0
	v_cmp_lt_f32_e32 vcc, 0x41000000, v122
	s_cmp_eq_u32 s71, 0
	s_cbranch_scc1 .Lat1_u2_first
	s_cbranch_vccz .Lat1_u2_norescale
	s_branch .Lat1_u2_rescale

; #define LAS __attribute__((address_space(3)))
; __device__ __forceinline__ unsigned pk2(float lo, float hi) { f32x2 v = {lo, hi}; bf16x2_t b = __builtin_convertvector(v, bf16x2_t); return __builtin_bit_cast(unsigned, b); }
; __device__ __forceinline__ s16x4 vtr(LAS const unsigned char* p) { return __builtin_bit_cast(s16x4, __builtin_amdgcn_ds_read_tr16_b64_v4i16((LAS v4i16_t*)p)); }
; __device__ __forceinline__ bf16x8 cat8(s16x4 a, s16x4 b) { return (bf16x8){a[0], a[1], a[2], a[3], b[0], b[1], b[2], b[3]}; }
; __device__ __forceinline__ void attn_block(LAS unsigned char* lds, const bf16_t* P, bf16_t* mix, int b, int h, int qb, float lam, float outscale, const float* subln) {
;     ...
;             for (int ks = 0; ks < 4; ++ks) { ka[ks][0] = *(const LAS bf16x8*)(Kb + kbase[ks]); ka[ks][1] = *(const LAS bf16x8*)(Kb + kbase[ks] + 8192); }
;     ...
; #pragma unroll
;             for (int j = 0; j < 16; ++j) { s0[j] = __builtin_amdgcn_exp2f(s0[j] - mrun); s1[j] = __builtin_amdgcn_exp2f(s1[j] - mrun); }
;             float ps0 = 0.f, ps1 = 0.f, ps2 = 0.f, ps3 = 0.f;
; #pragma unroll
;             for (int j = 0; j < 16; j += 2) { ps0 += s0[j]; ps1 += s1[j]; ps2 += s0[j + 1]; ps3 += s1[j + 1]; }
;             lrun += (ps0 + ps1) + (ps2 + ps3);
;             bf16x8 pb[4];
; #pragma unroll
;             for (int s2 = 0; s2 < 2; ++s2) {
;                 u32x4 w0, w1;
;                 w0.x = pk2(s0[8 * s2 + 0], s0[8 * s2 + 1]); w0.y = pk2(s0[8 * s2 + 2], s0[8 * s2 + 3]); w0.z = pk2(s0[8 * s2 + 4], s0[8 * s2 + 5]); w0.w = pk2(s0[8 * s2 + 6], s0[8 * s2 + 7]);
;                 w1.x = pk2(s1[8 * s2 + 0], s1[8 * s2 + 1]); w1.y = pk2(s1[8 * s2 + 2], s1[8 * s2 + 3]); w1.z = pk2(s1[8 * s2 + 4], s1[8 * s2 + 5]); w1.w = pk2(s1[8 * s2 + 6], s1[8 * s2 + 7]);
;                 pb[s2] = __builtin_bit_cast(bf16x8, w0); pb[2 + s2] = __builtin_bit_cast(bf16x8, w1);
;             }
; #pragma unroll
;             for (int s = 0; s < 4; ++s) {
; #pragma unroll
;                 for (int c = 0; c < 4; ++c) {
;                     const s16x4 v0 = vtr(Vb + vbase[c][0] + 4096 * s);
;                     const s16x4 v1 = vtr(Vb + vbase[c][1] + 4096 * s);
;                     o[c] = __builtin_amdgcn_mfma_f32_32x32x16_bf16(cat8(v0, v1), pb[s], o[c], 0, 0, 0);
;                 }
;             }
.Lat1_u2_norescale:
	v_exp_f32_e32 v82, v82
	v_exp_f32_e32 v83, v83
	v_exp_f32_e32 v84, v84
	v_exp_f32_e32 v85, v85
	v_exp_f32_e32 v86, v86
	v_exp_f32_e32 v87, v87
	v_exp_f32_e32 v88, v88
	v_exp_f32_e32 v89, v89
	v_exp_f32_e32 v90, v90
	v_exp_f32_e32 v91, v91
	v_exp_f32_e32 v92, v92
	v_exp_f32_e32 v93, v93
	v_exp_f32_e32 v94, v94
	v_exp_f32_e32 v95, v95
	v_exp_f32_e32 v96, v96
	v_exp_f32_e32 v97, v97
	v_cvt_pk_bf16_f32 v184, v82, v83
	v_cvt_pk_bf16_f32 v185, v84, v85
	v_cvt_pk_bf16_f32 v186, v86, v87
	v_cvt_pk_bf16_f32 v187, v88, v89
	v_cvt_pk_bf16_f32 v188, v90, v91
	v_cvt_pk_bf16_f32 v189, v92, v93
	v_cvt_pk_bf16_f32 v190, v94, v95
	v_cvt_pk_bf16_f32 v191, v96, v97
	v_add_f32_e32 v122, v82, v83
	v_add_f32_e32 v123, v84, v85
	v_add_f32_e32 v122, v122, v86
	v_add_f32_e32 v123, v123, v87
	v_add_f32_e32 v122, v122, v88
	v_add_f32_e32 v123, v123, v89
	v_add_f32_e32 v122, v122, v123
	v_add_f32_e32 v167, v167, v122
	v_add_f32_e32 v124, v90, v91
	v_add_f32_e32 v125, v92, v93
	v_add_f32_e32 v124, v124, v94
	v_add_f32_e32 v125, v125, v95
	v_add_f32_e32 v124, v124, v96
	v_add_f32_e32 v125, v125, v97
	v_add_f32_e32 v124, v124, v125
	v_add_f32_e32 v167, v167, v124
	s_waitcnt lgkmcnt(8)
	v_mfma_f32_32x32x16_bf16 v[50:65], v[136:139], v[184:187], v[50:65]
	ds_read_b64_tr_b16 v[246:247], v118 offset:36864
	ds_read_b64_tr_b16 v[248:249], v119 offset:36864
	v_exp_f32_e32 v66, v66
	v_exp_f32_e32 v67, v67
	v_exp_f32_e32 v68, v68
	v_mfma_f32_32x32x16_bf16 v[34:49], v[140:143], v[184:187], v[34:49]
	ds_read_b64_tr_b16 v[250:251], v120 offset:36864
	ds_read_b64_tr_b16 v[252:253], v121 offset:36864
	v_exp_f32_e32 v69, v69
	v_exp_f32_e32 v70, v70
	v_exp_f32_e32 v71, v71
	s_add_i32 m0, s73, 0xb800
	s_nop 0
	global_load_lds_dwordx4 v[134:135], off offset:2048
	s_waitcnt lgkmcnt(8)
	v_mfma_f32_32x32x16_bf16 v[18:33], v[204:207], v[184:187], v[18:33]
	ds_read_b64_tr_b16 v[136:137], v114 offset:40960
	ds_read_b64_tr_b16 v[138:139], v115 offset:40960
	v_exp_f32_e32 v72, v72
	v_exp_f32_e32 v73, v73
	v_cvt_pk_bf16_f32 v192, v66, v67
	v_mfma_f32_32x32x16_bf16 v[2:17], v[208:211], v[184:187], v[2:17]
	ds_read_b64_tr_b16 v[140:141], v116 offset:40960
	ds_read_b64_tr_b16 v[142:143], v117 offset:40960
	v_cvt_pk_bf16_f32 v193, v68, v69
	v_cvt_pk_bf16_f32 v194, v70, v71
	v_cvt_pk_bf16_f32 v195, v72, v73
	s_add_i32 m0, s73, 0xd800
	s_nop 0
	global_load_lds_dwordx4 v[200:201], off offset:2048
	v_lshl_add_u64 v[134:135], v[134:135], 0, s[40:41]
	v_lshl_add_u64 v[200:201], v[200:201], 0, s[40:41]
	s_waitcnt lgkmcnt(8)
	v_mfma_f32_32x32x16_bf16 v[50:65], v[238:241], v[188:191], v[50:65]
	ds_read_b64_tr_b16 v[204:205], v118 offset:40960
	ds_read_b64_tr_b16 v[206:207], v119 offset:40960
	v_exp_f32_e32 v74, v74
	v_exp_f32_e32 v75, v75
	v_exp_f32_e32 v76, v76
	v_mfma_f32_32x32x16_bf16 v[34:49], v[242:245], v[188:191], v[34:49]
	ds_read_b64_tr_b16 v[208:209], v120 offset:40960
	ds_read_b64_tr_b16 v[210:211], v121 offset:40960
	v_exp_f32_e32 v77, v77
	v_exp_f32_e32 v78, v78
	v_exp_f32_e32 v79, v79
	s_waitcnt lgkmcnt(8)
	v_mfma_f32_32x32x16_bf16 v[18:33], v[246:249], v[188:191], v[18:33]
	ds_read_b64_tr_b16 v[238:239], v114 offset:45056
	ds_read_b64_tr_b16 v[240:241], v115 offset:45056
	v_exp_f32_e32 v80, v80
	v_exp_f32_e32 v81, v81
	v_cvt_pk_bf16_f32 v196, v74, v75
	v_mfma_f32_32x32x16_bf16 v[2:17], v[250:253], v[188:191], v[2:17]
	ds_read_b64_tr_b16 v[242:243], v116 offset:45056
	ds_read_b64_tr_b16 v[244:245], v117 offset:45056
	v_cvt_pk_bf16_f32 v197, v76, v77
	v_cvt_pk_bf16_f32 v198, v78, v79
	v_cvt_pk_bf16_f32 v199, v80, v81
	s_waitcnt lgkmcnt(8)
	v_mfma_f32_32x32x16_bf16 v[50:65], v[136:139], v[192:195], v[50:65]
	ds_read_b64_tr_b16 v[246:247], v118 offset:45056
	ds_read_b64_tr_b16 v[248:249], v119 offset:45056
	v_add_f32_e32 v0, v66, v67
	v_add_f32_e32 v203, v68, v69
	v_add_f32_e32 v0, v0, v70
	v_mfma_f32_32x32x16_bf16 v[34:49], v[140:143], v[192:195], v[34:49]
	ds_read_b64_tr_b16 v[250:251], v120 offset:45056
	ds_read_b64_tr_b16 v[252:253], v121 offset:45056
	v_add_f32_e32 v203, v203, v71
	v_add_f32_e32 v0, v0, v72
	v_add_f32_e32 v203, v203, v73
	s_waitcnt lgkmcnt(8)
	v_mfma_f32_32x32x16_bf16 v[18:33], v[204:207], v[192:195], v[18:33]
	v_add_f32_e32 v0, v0, v203
	v_add_f32_e32 v167, v167, v0
	v_add_f32_e32 v0, v74, v75
	ds_read_b128 v[136:139], v126 offset:16384
	ds_read_b128 v[140:143], v126 offset:24576
	v_mfma_f32_32x32x16_bf16 v[2:17], v[208:211], v[192:195], v[2:17]
	v_add_f32_e32 v203, v76, v77
	v_add_f32_e32 v0, v0, v78
	v_add_f32_e32 v203, v203, v79
	ds_read_b128 v[204:207], v127 offset:16384
	ds_read_b128 v[208:211], v127 offset:24576
	s_waitcnt lgkmcnt(8)
	v_mfma_f32_32x32x16_bf16 v[50:65], v[238:241], v[196:199], v[50:65]
	v_add_f32_e32 v0, v0, v80
	v_add_f32_e32 v203, v203, v81
	v_add_f32_e32 v0, v0, v203
	v_mfma_f32_32x32x16_bf16 v[34:49], v[242:245], v[196:199], v[34:49]
	v_add_f32_e32 v167, v167, v0
	ds_read_b128 v[238:241], v128 offset:16384
	ds_read_b128 v[242:245], v128 offset:24576
	s_waitcnt lgkmcnt(6)
	v_mfma_f32_32x32x16_bf16 v[18:33], v[246:249], v[196:199], v[18:33]
	v_mfma_f32_32x32x16_bf16 v[2:17], v[250:253], v[196:199], v[2:17]
	ds_read_b128 v[246:249], v129 offset:16384
	ds_read_b128 v[250:253], v129 offset:24576
	s_waitcnt vmcnt(6)
	s_add_i32 s71, s71, 64
	s_barrier
; #define LAS __attribute__((address_space(3)))
; __device__ __forceinline__ float max3f(float a, float b, float c) { float r; asm("v_max3_f32 %0, %1, %2, %3" : "=v"(r) : "v"(a), "v"(b), "v"(c)); return r; }
; __device__ __forceinline__ void attn_block(LAS unsigned char* lds, const bf16_t* P, bf16_t* mix, int b, int h, int qb, float lam, float outscale, const float* subln) {
;     ...
;         const int kb = 64 * kt;
;         if (kb <= qw0 + 31) {
;             LAS const unsigned char* Kb = lds + ATT_K0 + buf * 16384;
;             LAS const unsigned char* Vb = lds + ATT_V0 + buf * 16384;
;             f32x16 s0, s1;
; #pragma unroll
;             for (int j = 0; j < 16; ++j) { s0[j] = 0.f; s1[j] = 0.f; }
;             bf16x8 ka[4][2];
; #pragma unroll
;             for (int ks = 0; ks < 4; ++ks) { ka[ks][0] = *(const LAS bf16x8*)(Kb + kbase[ks]); ka[ks][1] = *(const LAS bf16x8*)(Kb + kbase[ks] + 8192); }
;             __builtin_amdgcn_sched_barrier(0);
; #pragma unroll
;             for (int ks = 0; ks < 4; ++ks) {
;                 s0 = __builtin_amdgcn_mfma_f32_32x32x16_bf16(ka[ks][0], qf[ks], s0, 0, 0, 0);
;                 s1 = __builtin_amdgcn_mfma_f32_32x32x16_bf16(ka[ks][1], qf[ks], s1, 0, 0, 0);
;             }
;             if (kb + 63 > qw0) {
; #pragma unroll
;                 for (int j = 0; j < 16; ++j) { const int key = kb + crow(j, hi); if (key > qrow) s0[j] = -INFINITY; if (key + 32 > qrow) s1[j] = -INFINITY; }
;             }
;             float mxa = max3f(s0[0], s1[0], s0[1]), mxb = max3f(s1[1], s0[2], s1[2]), mxc = max3f(s0[3], s1[3], s0[4]), mxd = max3f(s1[4], s0[5], s1[5]);
;             mxa = max3f(mxa, s0[6], s1[6]); mxb = max3f(mxb, s0[7], s1[7]); mxc = max3f(mxc, s0[8], s1[8]); mxd = max3f(mxd, s0[9], s1[9]);
;             mxa = max3f(mxa, s0[10], s1[10]); mxb = max3f(mxb, s0[11], s1[11]); mxc = max3f(mxc, s0[12], s1[12]); mxd = max3f(mxd, s0[13], s1[13]);
;             mxa = max3f(mxa, s0[14], s1[14]); mxb = max3f(mxb, s0[15], s1[15]);
;             float mx = max3f(mxa, mxb, max3f(mxc, mxd, mxd));
;             { auto rr = __builtin_amdgcn_permlane32_swap(__builtin_bit_cast(unsigned, mx), __builtin_bit_cast(unsigned, mx), false, false);
;               mx = fmaxf(__builtin_bit_cast(float, rr[0]), __builtin_bit_cast(float, rr[1])); }
;             if (__any(mx > mrun + 8.0f)) {
	s_waitcnt lgkmcnt(6)
	v_mfma_f32_32x32x16_bf16 v[82:97], v[136:139], v[110:113], v[222:237]
	v_mfma_f32_32x32x16_bf16 v[66:81], v[140:143], v[110:113], v[222:237]
	s_waitcnt lgkmcnt(4)
	v_mfma_f32_32x32x16_bf16 v[82:97], v[204:207], v[106:109], v[82:97]
	v_mfma_f32_32x32x16_bf16 v[66:81], v[208:211], v[106:109], v[66:81]
	s_waitcnt lgkmcnt(2)
	v_mfma_f32_32x32x16_bf16 v[82:97], v[238:241], v[102:105], v[82:97]
	v_mfma_f32_32x32x16_bf16 v[66:81], v[242:245], v[102:105], v[66:81]
	s_waitcnt lgkmcnt(0)
	v_mfma_f32_32x32x16_bf16 v[82:97], v[246:249], v[98:101], v[82:97]
	v_mfma_f32_32x32x16_bf16 v[66:81], v[250:253], v[98:101], v[66:81]
	s_add_i32 m0, s73, 0x10000
	s_nop 0
	global_load_lds_dwordx4 v[134:135], off
	s_add_i32 m0, s73, 0x12000
	s_nop 0
	global_load_lds_dwordx4 v[200:201], off
	ds_read_b64_tr_b16 v[136:137], v114 offset:49152
	ds_read_b64_tr_b16 v[138:139], v115 offset:49152
	ds_read_b64_tr_b16 v[140:141], v116 offset:49152
	ds_read_b64_tr_b16 v[142:143], v117 offset:49152
	ds_read_b64_tr_b16 v[204:205], v118 offset:49152
	ds_read_b64_tr_b16 v[206:207], v119 offset:49152
	ds_read_b64_tr_b16 v[208:209], v120 offset:49152
	ds_read_b64_tr_b16 v[210:211], v121 offset:49152
	ds_read_b64_tr_b16 v[238:239], v114 offset:53248
	ds_read_b64_tr_b16 v[240:241], v115 offset:53248
	ds_read_b64_tr_b16 v[242:243], v116 offset:53248
	ds_read_b64_tr_b16 v[244:245], v117 offset:53248
	v_max3_f32 v122, v82, v66, v83
	v_max3_f32 v123, v67, v84, v68
	v_max3_f32 v124, v85, v69, v86
	v_max3_f32 v125, v70, v87, v71
	v_max3_f32 v122, v122, v88, v72
	v_max3_f32 v123, v123, v89, v73
	v_max3_f32 v124, v124, v90, v74
	v_max3_f32 v125, v125, v91, v75
	v_max3_f32 v122, v122, v92, v76
	v_max3_f32 v123, v123, v93, v77
	v_max3_f32 v124, v124, v94, v78
	v_max3_f32 v125, v125, v95, v79
	v_max3_f32 v122, v122, v96, v80
	v_max3_f32 v123, v123, v97, v81
	v_max3_f32 v122, v122, v123, v124
	v_max_f32_e32 v122, v122, v125
	v_mov_b32_e32 v203, v122
	s_nop 1
	v_permlane32_swap_b32_e32 v122, v203
	s_nop 1
	v_max_f32_e32 v122, v122, v203
	s_mov_b32 s70, 0
	v_cmp_lt_f32_e32 vcc, 0x41000000, v122
	s_cmp_eq_u32 s71, 0
	s_cbranch_scc1 .Lat1_u3_first
	s_cbranch_vccz .Lat1_u3_norescale
	s_branch .Lat1_u3_rescale

; __device__ __forceinline__ unsigned pk2(float lo, float hi) { f32x2 v = {lo, hi}; bf16x2_t b = __builtin_convertvector(v, bf16x2_t); return __builtin_bit_cast(unsigned, b); }
; __device__ __forceinline__ s16x4 vtr(LAS const unsigned char* p) { return __builtin_bit_cast(s16x4, __builtin_amdgcn_ds_read_tr16_b64_v4i16((LAS v4i16_t*)p)); }
; __device__ __forceinline__ bf16x8 cat8(s16x4 a, s16x4 b) { return (bf16x8){a[0], a[1], a[2], a[3], b[0], b[1], b[2], b[3]}; }
; __device__ __forceinline__ void attn_block(LAS unsigned char* lds, const bf16_t* P, bf16_t* mix, int b, int h, int qb, float lam, float outscale, const float* subln) {
;     ...
;     for (int kt = 0; kt < ntiles; ++kt) {
;     ...
; #pragma unroll
;             for (int j = 0; j < 16; ++j) { s0[j] = __builtin_amdgcn_exp2f(s0[j] - mrun); s1[j] = __builtin_amdgcn_exp2f(s1[j] - mrun); }
;             float ps0 = 0.f, ps1 = 0.f, ps2 = 0.f, ps3 = 0.f;
; #pragma unroll
;             for (int j = 0; j < 16; j += 2) { ps0 += s0[j]; ps1 += s1[j]; ps2 += s0[j + 1]; ps3 += s1[j + 1]; }
;             lrun += (ps0 + ps1) + (ps2 + ps3);
;             bf16x8 pb[4];
; #pragma unroll
;             for (int s2 = 0; s2 < 2; ++s2) {
;                 u32x4 w0, w1;
;                 w0.x = pk2(s0[8 * s2 + 0], s0[8 * s2 + 1]); w0.y = pk2(s0[8 * s2 + 2], s0[8 * s2 + 3]); w0.z = pk2(s0[8 * s2 + 4], s0[8 * s2 + 5]); w0.w = pk2(s0[8 * s2 + 6], s0[8 * s2 + 7]);
;                 w1.x = pk2(s1[8 * s2 + 0], s1[8 * s2 + 1]); w1.y = pk2(s1[8 * s2 + 2], s1[8 * s2 + 3]); w1.z = pk2(s1[8 * s2 + 4], s1[8 * s2 + 5]); w1.w = pk2(s1[8 * s2 + 6], s1[8 * s2 + 7]);
;                 pb[s2] = __builtin_bit_cast(bf16x8, w0); pb[2 + s2] = __builtin_bit_cast(bf16x8, w1);
;             }
; #pragma unroll
;             for (int s = 0; s < 4; ++s) {
; #pragma unroll
;                 for (int c = 0; c < 4; ++c) {
;                     const s16x4 v0 = vtr(Vb + vbase[c][0] + 4096 * s);
;                     const s16x4 v1 = vtr(Vb + vbase[c][1] + 4096 * s);
;                     o[c] = __builtin_amdgcn_mfma_f32_32x32x16_bf16(cat8(v0, v1), pb[s], o[c], 0, 0, 0);
;                 }
;             }
.Lat1_u3_norescale:
	v_exp_f32_e32 v82, v82
	v_exp_f32_e32 v83, v83
	v_exp_f32_e32 v84, v84
	v_exp_f32_e32 v85, v85
	v_exp_f32_e32 v86, v86
	v_exp_f32_e32 v87, v87
	v_exp_f32_e32 v88, v88
	v_exp_f32_e32 v89, v89
	v_exp_f32_e32 v90, v90
	v_exp_f32_e32 v91, v91
	v_exp_f32_e32 v92, v92
	v_exp_f32_e32 v93, v93
	v_exp_f32_e32 v94, v94
	v_exp_f32_e32 v95, v95
	v_exp_f32_e32 v96, v96
	v_exp_f32_e32 v97, v97
	v_cvt_pk_bf16_f32 v184, v82, v83
	v_cvt_pk_bf16_f32 v185, v84, v85
	v_cvt_pk_bf16_f32 v186, v86, v87
	v_cvt_pk_bf16_f32 v187, v88, v89
	v_cvt_pk_bf16_f32 v188, v90, v91
	v_cvt_pk_bf16_f32 v189, v92, v93
	v_cvt_pk_bf16_f32 v190, v94, v95
	v_cvt_pk_bf16_f32 v191, v96, v97
	v_add_f32_e32 v122, v82, v83
	v_add_f32_e32 v123, v84, v85
	v_add_f32_e32 v122, v122, v86
	v_add_f32_e32 v123, v123, v87
	v_add_f32_e32 v122, v122, v88
	v_add_f32_e32 v123, v123, v89
	v_add_f32_e32 v122, v122, v123
	v_add_f32_e32 v167, v167, v122
	v_add_f32_e32 v124, v90, v91
	v_add_f32_e32 v125, v92, v93
	v_add_f32_e32 v124, v124, v94
	v_add_f32_e32 v125, v125, v95
	v_add_f32_e32 v124, v124, v96
	v_add_f32_e32 v125, v125, v97
	v_add_f32_e32 v124, v124, v125
	v_add_f32_e32 v167, v167, v124
	s_waitcnt lgkmcnt(8)
	v_mfma_f32_32x32x16_bf16 v[50:65], v[136:139], v[184:187], v[50:65]
	ds_read_b64_tr_b16 v[246:247], v118 offset:53248
	ds_read_b64_tr_b16 v[248:249], v119 offset:53248
	v_exp_f32_e32 v66, v66
	v_exp_f32_e32 v67, v67
	v_exp_f32_e32 v68, v68
	v_mfma_f32_32x32x16_bf16 v[34:49], v[140:143], v[184:187], v[34:49]
	ds_read_b64_tr_b16 v[250:251], v120 offset:53248
	ds_read_b64_tr_b16 v[252:253], v121 offset:53248
	v_exp_f32_e32 v69, v69
	v_exp_f32_e32 v70, v70
	v_exp_f32_e32 v71, v71
	s_add_i32 m0, s73, 0x17800
	s_nop 0
	global_load_lds_dwordx4 v[134:135], off offset:2048
	s_waitcnt lgkmcnt(8)
	v_mfma_f32_32x32x16_bf16 v[18:33], v[204:207], v[184:187], v[18:33]
	ds_read_b64_tr_b16 v[136:137], v114 offset:57344
	ds_read_b64_tr_b16 v[138:139], v115 offset:57344
	v_exp_f32_e32 v72, v72
	v_exp_f32_e32 v73, v73
	v_cvt_pk_bf16_f32 v192, v66, v67
	v_mfma_f32_32x32x16_bf16 v[2:17], v[208:211], v[184:187], v[2:17]
	ds_read_b64_tr_b16 v[140:141], v116 offset:57344
	ds_read_b64_tr_b16 v[142:143], v117 offset:57344
	v_cvt_pk_bf16_f32 v193, v68, v69
	v_cvt_pk_bf16_f32 v194, v70, v71
	v_cvt_pk_bf16_f32 v195, v72, v73
	s_add_i32 m0, s73, 0x19800
	s_nop 0
	global_load_lds_dwordx4 v[200:201], off offset:2048
	v_lshl_add_u64 v[134:135], v[134:135], 0, s[40:41]
	v_lshl_add_u64 v[200:201], v[200:201], 0, s[40:41]
	s_waitcnt lgkmcnt(8)
	v_mfma_f32_32x32x16_bf16 v[50:65], v[238:241], v[188:191], v[50:65]
	ds_read_b64_tr_b16 v[204:205], v118 offset:57344
	ds_read_b64_tr_b16 v[206:207], v119 offset:57344
	v_exp_f32_e32 v74, v74
	v_exp_f32_e32 v75, v75
	v_exp_f32_e32 v76, v76
	v_mfma_f32_32x32x16_bf16 v[34:49], v[242:245], v[188:191], v[34:49]
	ds_read_b64_tr_b16 v[208:209], v120 offset:57344
	ds_read_b64_tr_b16 v[210:211], v121 offset:57344
	v_exp_f32_e32 v77, v77
	v_exp_f32_e32 v78, v78
	v_exp_f32_e32 v79, v79
	s_waitcnt lgkmcnt(8)
	v_mfma_f32_32x32x16_bf16 v[18:33], v[246:249], v[188:191], v[18:33]
	ds_read_b64_tr_b16 v[238:239], v114 offset:61440
	ds_read_b64_tr_b16 v[240:241], v115 offset:61440
	v_exp_f32_e32 v80, v80
	v_exp_f32_e32 v81, v81
	v_cvt_pk_bf16_f32 v196, v74, v75
	v_mfma_f32_32x32x16_bf16 v[2:17], v[250:253], v[188:191], v[2:17]
	ds_read_b64_tr_b16 v[242:243], v116 offset:61440
	ds_read_b64_tr_b16 v[244:245], v117 offset:61440
	v_cvt_pk_bf16_f32 v197, v76, v77
	v_cvt_pk_bf16_f32 v198, v78, v79
	v_cvt_pk_bf16_f32 v199, v80, v81
	s_waitcnt lgkmcnt(8)
	v_mfma_f32_32x32x16_bf16 v[50:65], v[136:139], v[192:195], v[50:65]
	ds_read_b64_tr_b16 v[246:247], v118 offset:61440
	ds_read_b64_tr_b16 v[248:249], v119 offset:61440
	v_add_f32_e32 v0, v66, v67
	v_add_f32_e32 v203, v68, v69
	v_add_f32_e32 v0, v0, v70
	v_mfma_f32_32x32x16_bf16 v[34:49], v[140:143], v[192:195], v[34:49]
	ds_read_b64_tr_b16 v[250:251], v120 offset:61440
	ds_read_b64_tr_b16 v[252:253], v121 offset:61440
	v_add_f32_e32 v203, v203, v71
	v_add_f32_e32 v0, v0, v72
	v_add_f32_e32 v203, v203, v73
	s_waitcnt lgkmcnt(8)
	v_mfma_f32_32x32x16_bf16 v[18:33], v[204:207], v[192:195], v[18:33]
	v_add_f32_e32 v0, v0, v203
	v_add_f32_e32 v167, v167, v0
	v_add_f32_e32 v0, v74, v75
	ds_read_b128 v[136:139], v180 offset:0
	ds_read_b128 v[140:143], v180 offset:8192
	v_mfma_f32_32x32x16_bf16 v[2:17], v[208:211], v[192:195], v[2:17]
	v_add_f32_e32 v203, v76, v77
	v_add_f32_e32 v0, v0, v78
	v_add_f32_e32 v203, v203, v79
	ds_read_b128 v[204:207], v181 offset:0
	ds_read_b128 v[208:211], v181 offset:8192
	s_waitcnt lgkmcnt(8)
	v_mfma_f32_32x32x16_bf16 v[50:65], v[238:241], v[196:199], v[50:65]
	v_add_f32_e32 v0, v0, v80
	v_add_f32_e32 v203, v203, v81
	v_add_f32_e32 v0, v0, v203
	v_mfma_f32_32x32x16_bf16 v[34:49], v[242:245], v[196:199], v[34:49]
	v_add_f32_e32 v167, v167, v0
	ds_read_b128 v[238:241], v178 offset:0
	ds_read_b128 v[242:245], v178 offset:8192
	s_waitcnt lgkmcnt(6)
	v_mfma_f32_32x32x16_bf16 v[18:33], v[246:249], v[196:199], v[18:33]
	v_mfma_f32_32x32x16_bf16 v[2:17], v[250:253], v[196:199], v[2:17]
	ds_read_b128 v[246:249], v177 offset:0
	ds_read_b128 v[250:253], v177 offset:8192
	s_waitcnt vmcnt(6)
	s_add_i32 s71, s71, 64
	s_add_i32 s72, s71, 384
	s_cmp_le_u32 s72, s36
	s_barrier
	s_cbranch_scc1 .Lat1_U_top

; #define LAS __attribute__((address_space(3)))
; __device__ __forceinline__ void attn_block(LAS unsigned char* lds, const bf16_t* P, bf16_t* mix, int b, int h, int qb, float lam, float outscale, const float* subln) {
;     ...
;     for (int kt = 0; kt < ntiles; ++kt) {
;         __syncthreads();
;         const int buf = kt & 1;
;         if (kt + 1 < ntiles) {
;             const size_t ro = (size_t)(64 * (kt + 1)) * INC;
;             kr0 = *(const u32x4*)(kg + ro + (size_t)srow * INC); kr1 = *(const u32x4*)(kg + ro + (size_t)(srow + 32) * INC);
;             vr0 = *(const u32x4*)(vg + ro + (size_t)srow * INC); vr1 = *(const u32x4*)(vg + ro + (size_t)(srow + 32) * INC);
;         }
;         const int kb = 64 * kt;
;         if (kb <= qw0 + 31) {
;             LAS const unsigned char* Kb = lds + ATT_K0 + buf * 16384;
;             LAS const unsigned char* Vb = lds + ATT_V0 + buf * 16384;
;             f32x16 s0, s1;
; #pragma unroll
;             for (int j = 0; j < 16; ++j) { s0[j] = 0.f; s1[j] = 0.f; }
;             bf16x8 ka[4][2];
; #pragma unroll
;             for (int ks = 0; ks < 4; ++ks) { ka[ks][0] = *(const LAS bf16x8*)(Kb + kbase[ks]); ka[ks][1] = *(const LAS bf16x8*)(Kb + kbase[ks] + 8192); }
;             __builtin_amdgcn_sched_barrier(0);
; #pragma unroll
;             for (int ks = 0; ks < 4; ++ks) {
;                 s0 = __builtin_amdgcn_mfma_f32_32x32x16_bf16(ka[ks][0], qf[ks], s0, 0, 0, 0);
;                 s1 = __builtin_amdgcn_mfma_f32_32x32x16_bf16(ka[ks][1], qf[ks], s1, 0, 0, 0);
;             }
;             if (kb + 63 > qw0) {
; #pragma unroll
;                 for (int j = 0; j < 16; ++j) { const int key = kb + crow(j, hi); if (key > qrow) s0[j] = -INFINITY; if (key + 32 > qrow) s1[j] = -INFINITY; }
;             }
;             float mxa = max3f(s0[0], s1[0], s0[1]), mxb = max3f(s1[1], s0[2], s1[2]), mxc = max3f(s0[3], s1[3], s0[4]), mxd = max3f(s1[4], s0[5], s1[5]);
;             mxa = max3f(mxa, s0[6], s1[6]); mxb = max3f(mxb, s0[7], s1[7]); mxc = max3f(mxc, s0[8], s1[8]); mxd = max3f(mxd, s0[9], s1[9]);
;             mxa = max3f(mxa, s0[10], s1[10]); mxb = max3f(mxb, s0[11], s1[11]); mxc = max3f(mxc, s0[12], s1[12]); mxd = max3f(mxd, s0[13], s1[13]);
;             mxa = max3f(mxa, s0[14], s1[14]); mxb = max3f(mxb, s0[15], s1[15]);
;             float mx = max3f(mxa, mxb, max3f(mxc, mxd, mxd));
.Lat2_U_top:
	s_waitcnt lgkmcnt(6)
	v_mfma_f32_32x32x16_bf16 v[82:97], v[136:139], v[110:113], v[222:237]
	v_mfma_f32_32x32x16_bf16 v[66:81], v[140:143], v[110:113], v[222:237]
	s_waitcnt lgkmcnt(4)
	v_mfma_f32_32x32x16_bf16 v[82:97], v[204:207], v[106:109], v[82:97]
	v_mfma_f32_32x32x16_bf16 v[66:81], v[208:211], v[106:109], v[66:81]
	s_waitcnt lgkmcnt(2)
	v_mfma_f32_32x32x16_bf16 v[82:97], v[238:241], v[102:105], v[82:97]
	v_mfma_f32_32x32x16_bf16 v[66:81], v[242:245], v[102:105], v[66:81]
	s_waitcnt lgkmcnt(0)
	v_mfma_f32_32x32x16_bf16 v[82:97], v[246:249], v[98:101], v[82:97]
	v_mfma_f32_32x32x16_bf16 v[66:81], v[250:253], v[98:101], v[66:81]
	s_add_i32 m0, s62, 0x14000
	s_nop 0
	global_load_lds_dwordx4 v[134:135], off
	s_add_i32 m0, s62, 0x16000
	s_nop 0
	global_load_lds_dwordx4 v[200:201], off
	ds_read_b64_tr_b16 v[136:137], v168 offset:32768
	ds_read_b64_tr_b16 v[138:139], v175 offset:32768
	ds_read_b64_tr_b16 v[140:141], v172 offset:32768
	ds_read_b64_tr_b16 v[142:143], v174 offset:32768
	ds_read_b64_tr_b16 v[204:205], v170 offset:32768
	ds_read_b64_tr_b16 v[206:207], v173 offset:32768
	ds_read_b64_tr_b16 v[208:209], v169 offset:32768
	ds_read_b64_tr_b16 v[210:211], v171 offset:32768
	ds_read_b64_tr_b16 v[238:239], v168 offset:36864
	ds_read_b64_tr_b16 v[240:241], v175 offset:36864
	ds_read_b64_tr_b16 v[242:243], v172 offset:36864
	ds_read_b64_tr_b16 v[244:245], v174 offset:36864
	v_max3_f32 v122, v82, v66, v83
	v_max3_f32 v123, v67, v84, v68
	v_max3_f32 v124, v85, v69, v86
	v_max3_f32 v125, v70, v87, v71
	v_max3_f32 v122, v122, v88, v72
	v_max3_f32 v123, v123, v89, v73
	v_max3_f32 v124, v124, v90, v74
	v_max3_f32 v125, v125, v91, v75
	v_max3_f32 v122, v122, v92, v76
	v_max3_f32 v123, v123, v93, v77
	v_max3_f32 v124, v124, v94, v78
	v_max3_f32 v125, v125, v95, v79
	v_max3_f32 v122, v122, v96, v80
	v_max3_f32 v123, v123, v97, v81
	v_max3_f32 v122, v122, v123, v124
	v_max_f32_e32 v122, v122, v125
	v_mov_b32_e32 v203, v122
	s_nop 1
	v_permlane32_swap_b32_e32 v122, v203
	s_nop 1
	v_max_f32_e32 v122, v122, v203
	s_mov_b32 s39, 0
	v_cmp_lt_f32_e32 vcc, 0x41000000, v122
	s_cmp_eq_u32 s50, 0
	s_cbranch_scc1 .Lat2_u0_first
	s_cbranch_vccz .Lat2_u0_norescale
	s_branch .Lat2_u0_rescale

; #define LAS __attribute__((address_space(3)))
; __device__ __forceinline__ unsigned pk2(float lo, float hi) { f32x2 v = {lo, hi}; bf16x2_t b = __builtin_convertvector(v, bf16x2_t); return __builtin_bit_cast(unsigned, b); }
; __device__ __forceinline__ s16x4 vtr(LAS const unsigned char* p) { return __builtin_bit_cast(s16x4, __builtin_amdgcn_ds_read_tr16_b64_v4i16((LAS v4i16_t*)p)); }
; __device__ __forceinline__ bf16x8 cat8(s16x4 a, s16x4 b) { return (bf16x8){a[0], a[1], a[2], a[3], b[0], b[1], b[2], b[3]}; }
; __device__ __forceinline__ void attn_block(LAS unsigned char* lds, const bf16_t* P, bf16_t* mix, int b, int h, int qb, float lam, float outscale, const float* subln) {
;     ...
;             for (int ks = 0; ks < 4; ++ks) { ka[ks][0] = *(const LAS bf16x8*)(Kb + kbase[ks]); ka[ks][1] = *(const LAS bf16x8*)(Kb + kbase[ks] + 8192); }
;     ...
; #pragma unroll
;             for (int j = 0; j < 16; ++j) { s0[j] = __builtin_amdgcn_exp2f(s0[j] - mrun); s1[j] = __builtin_amdgcn_exp2f(s1[j] - mrun); }
;             float ps0 = 0.f, ps1 = 0.f, ps2 = 0.f, ps3 = 0.f;
; #pragma unroll
;             for (int j = 0; j < 16; j += 2) { ps0 += s0[j]; ps1 += s1[j]; ps2 += s0[j + 1]; ps3 += s1[j + 1]; }
;             lrun += (ps0 + ps1) + (ps2 + ps3);
;             bf16x8 pb[4];
; #pragma unroll
;             for (int s2 = 0; s2 < 2; ++s2) {
;                 u32x4 w0, w1;
;                 w0.x = pk2(s0[8 * s2 + 0], s0[8 * s2 + 1]); w0.y = pk2(s0[8 * s2 + 2], s0[8 * s2 + 3]); w0.z = pk2(s0[8 * s2 + 4], s0[8 * s2 + 5]); w0.w = pk2(s0[8 * s2 + 6], s0[8 * s2 + 7]);
;                 w1.x = pk2(s1[8 * s2 + 0], s1[8 * s2 + 1]); w1.y = pk2(s1[8 * s2 + 2], s1[8 * s2 + 3]); w1.z = pk2(s1[8 * s2 + 4], s1[8 * s2 + 5]); w1.w = pk2(s1[8 * s2 + 6], s1[8 * s2 + 7]);
;                 pb[s2] = __builtin_bit_cast(bf16x8, w0); pb[2 + s2] = __builtin_bit_cast(bf16x8, w1);
;             }
; #pragma unroll
;             for (int s = 0; s < 4; ++s) {
; #pragma unroll
;                 for (int c = 0; c < 4; ++c) {
;                     const s16x4 v0 = vtr(Vb + vbase[c][0] + 4096 * s);
;                     const s16x4 v1 = vtr(Vb + vbase[c][1] + 4096 * s);
;                     o[c] = __builtin_amdgcn_mfma_f32_32x32x16_bf16(cat8(v0, v1), pb[s], o[c], 0, 0, 0);
;                 }
;             }
.Lat2_u0_norescale:
	v_exp_f32_e32 v82, v82
	v_exp_f32_e32 v83, v83
	v_exp_f32_e32 v84, v84
	v_exp_f32_e32 v85, v85
	v_exp_f32_e32 v86, v86
	v_exp_f32_e32 v87, v87
	v_exp_f32_e32 v88, v88
	v_exp_f32_e32 v89, v89
	v_exp_f32_e32 v90, v90
	v_exp_f32_e32 v91, v91
	v_exp_f32_e32 v92, v92
	v_exp_f32_e32 v93, v93
	v_exp_f32_e32 v94, v94
	v_exp_f32_e32 v95, v95
	v_exp_f32_e32 v96, v96
	v_exp_f32_e32 v97, v97
	v_cvt_pk_bf16_f32 v184, v82, v83
	v_cvt_pk_bf16_f32 v185, v84, v85
	v_cvt_pk_bf16_f32 v186, v86, v87
	v_cvt_pk_bf16_f32 v187, v88, v89
	v_cvt_pk_bf16_f32 v188, v90, v91
	v_cvt_pk_bf16_f32 v189, v92, v93
	v_cvt_pk_bf16_f32 v190, v94, v95
	v_cvt_pk_bf16_f32 v191, v96, v97
	v_add_f32_e32 v122, v82, v83
	v_add_f32_e32 v123, v84, v85
	v_add_f32_e32 v122, v122, v86
	v_add_f32_e32 v123, v123, v87
	v_add_f32_e32 v122, v122, v88
	v_add_f32_e32 v123, v123, v89
	v_add_f32_e32 v122, v122, v123
	v_add_f32_e32 v167, v167, v122
	v_add_f32_e32 v124, v90, v91
	v_add_f32_e32 v125, v92, v93
	v_add_f32_e32 v124, v124, v94
	v_add_f32_e32 v125, v125, v95
	v_add_f32_e32 v124, v124, v96
	v_add_f32_e32 v125, v125, v97
	v_add_f32_e32 v124, v124, v125
	v_add_f32_e32 v167, v167, v124
	s_waitcnt lgkmcnt(8)
	v_mfma_f32_32x32x16_bf16 v[50:65], v[136:139], v[184:187], v[50:65]
	ds_read_b64_tr_b16 v[246:247], v170 offset:36864
	ds_read_b64_tr_b16 v[248:249], v173 offset:36864
	v_exp_f32_e32 v66, v66
	v_exp_f32_e32 v67, v67
	v_exp_f32_e32 v68, v68
	v_mfma_f32_32x32x16_bf16 v[34:49], v[140:143], v[184:187], v[34:49]
	ds_read_b64_tr_b16 v[250:251], v169 offset:36864
	ds_read_b64_tr_b16 v[252:253], v171 offset:36864
	v_exp_f32_e32 v69, v69
	v_exp_f32_e32 v70, v70
	v_exp_f32_e32 v71, v71
	s_add_i32 m0, s62, 0x1b800
	s_nop 0
	global_load_lds_dwordx4 v[134:135], off offset:2048
	s_waitcnt lgkmcnt(8)
	v_mfma_f32_32x32x16_bf16 v[18:33], v[204:207], v[184:187], v[18:33]
	ds_read_b64_tr_b16 v[136:137], v168 offset:40960
	ds_read_b64_tr_b16 v[138:139], v175 offset:40960
	v_exp_f32_e32 v72, v72
	v_exp_f32_e32 v73, v73
	v_cvt_pk_bf16_f32 v192, v66, v67
	v_mfma_f32_32x32x16_bf16 v[2:17], v[208:211], v[184:187], v[2:17]
	ds_read_b64_tr_b16 v[140:141], v172 offset:40960
	ds_read_b64_tr_b16 v[142:143], v174 offset:40960
	v_cvt_pk_bf16_f32 v193, v68, v69
	v_cvt_pk_bf16_f32 v194, v70, v71
	v_cvt_pk_bf16_f32 v195, v72, v73
	s_add_i32 m0, s62, 0x1d800
	s_nop 0
	global_load_lds_dwordx4 v[200:201], off offset:2048
	v_lshl_add_u64 v[134:135], v[134:135], 0, s[40:41]
	v_lshl_add_u64 v[200:201], v[200:201], 0, s[40:41]
	s_waitcnt lgkmcnt(8)
	v_mfma_f32_32x32x16_bf16 v[50:65], v[238:241], v[188:191], v[50:65]
	ds_read_b64_tr_b16 v[204:205], v170 offset:40960
	ds_read_b64_tr_b16 v[206:207], v173 offset:40960
	v_exp_f32_e32 v74, v74
	v_exp_f32_e32 v75, v75
	v_exp_f32_e32 v76, v76
	v_mfma_f32_32x32x16_bf16 v[34:49], v[242:245], v[188:191], v[34:49]
	ds_read_b64_tr_b16 v[208:209], v169 offset:40960
	ds_read_b64_tr_b16 v[210:211], v171 offset:40960
	v_exp_f32_e32 v77, v77
	v_exp_f32_e32 v78, v78
	v_exp_f32_e32 v79, v79
	s_waitcnt lgkmcnt(8)
	v_mfma_f32_32x32x16_bf16 v[18:33], v[246:249], v[188:191], v[18:33]
	ds_read_b64_tr_b16 v[238:239], v168 offset:45056
	ds_read_b64_tr_b16 v[240:241], v175 offset:45056
	v_exp_f32_e32 v80, v80
	v_exp_f32_e32 v81, v81
	v_cvt_pk_bf16_f32 v196, v74, v75
	v_mfma_f32_32x32x16_bf16 v[2:17], v[250:253], v[188:191], v[2:17]
	ds_read_b64_tr_b16 v[242:243], v172 offset:45056
	ds_read_b64_tr_b16 v[244:245], v174 offset:45056
	v_cvt_pk_bf16_f32 v197, v76, v77
	v_cvt_pk_bf16_f32 v198, v78, v79
	v_cvt_pk_bf16_f32 v199, v80, v81
	s_waitcnt lgkmcnt(8)
	v_mfma_f32_32x32x16_bf16 v[50:65], v[136:139], v[192:195], v[50:65]
	ds_read_b64_tr_b16 v[246:247], v170 offset:45056
	ds_read_b64_tr_b16 v[248:249], v173 offset:45056
	v_add_f32_e32 v0, v66, v67
	v_add_f32_e32 v203, v68, v69
	v_add_f32_e32 v0, v0, v70
	v_mfma_f32_32x32x16_bf16 v[34:49], v[140:143], v[192:195], v[34:49]
	ds_read_b64_tr_b16 v[250:251], v169 offset:45056
	ds_read_b64_tr_b16 v[252:253], v171 offset:45056
	v_add_f32_e32 v203, v203, v71
	v_add_f32_e32 v0, v0, v72
	v_add_f32_e32 v203, v203, v73
	s_waitcnt lgkmcnt(8)
	v_mfma_f32_32x32x16_bf16 v[18:33], v[204:207], v[192:195], v[18:33]
	v_add_f32_e32 v0, v0, v203
	v_add_f32_e32 v167, v167, v0
	v_add_f32_e32 v0, v74, v75
	ds_read_b128 v[136:139], v178 offset:16384
	ds_read_b128 v[140:143], v178 offset:24576
	v_mfma_f32_32x32x16_bf16 v[2:17], v[208:211], v[192:195], v[2:17]
	v_add_f32_e32 v203, v76, v77
	v_add_f32_e32 v0, v0, v78
	v_add_f32_e32 v203, v203, v79
	ds_read_b128 v[204:207], v181 offset:16384
	ds_read_b128 v[208:211], v181 offset:24576
	s_waitcnt lgkmcnt(8)
	v_mfma_f32_32x32x16_bf16 v[50:65], v[238:241], v[196:199], v[50:65]
	v_add_f32_e32 v0, v0, v80
	v_add_f32_e32 v203, v203, v81
	v_add_f32_e32 v0, v0, v203
	v_mfma_f32_32x32x16_bf16 v[34:49], v[242:245], v[196:199], v[34:49]
	v_add_f32_e32 v167, v167, v0
	ds_read_b128 v[238:241], v180 offset:16384
	ds_read_b128 v[242:245], v180 offset:24576
	s_waitcnt lgkmcnt(6)
	v_mfma_f32_32x32x16_bf16 v[18:33], v[246:249], v[196:199], v[18:33]
	v_mfma_f32_32x32x16_bf16 v[2:17], v[250:253], v[196:199], v[2:17]
	ds_read_b128 v[246:249], v179 offset:16384
	ds_read_b128 v[250:253], v179 offset:24576
	s_waitcnt vmcnt(6)
	s_add_i32 s50, s50, 64
	s_barrier
; #define LAS __attribute__((address_space(3)))
; __device__ __forceinline__ float max3f(float a, float b, float c) { float r; asm("v_max3_f32 %0, %1, %2, %3" : "=v"(r) : "v"(a), "v"(b), "v"(c)); return r; }
; __device__ __forceinline__ void attn_block(LAS unsigned char* lds, const bf16_t* P, bf16_t* mix, int b, int h, int qb, float lam, float outscale, const float* subln) {
;     ...
;         const int kb = 64 * kt;
;         if (kb <= qw0 + 31) {
;             LAS const unsigned char* Kb = lds + ATT_K0 + buf * 16384;
;             LAS const unsigned char* Vb = lds + ATT_V0 + buf * 16384;
;             f32x16 s0, s1;
; #pragma unroll
;             for (int j = 0; j < 16; ++j) { s0[j] = 0.f; s1[j] = 0.f; }
;             bf16x8 ka[4][2];
; #pragma unroll
;             for (int ks = 0; ks < 4; ++ks) { ka[ks][0] = *(const LAS bf16x8*)(Kb + kbase[ks]); ka[ks][1] = *(const LAS bf16x8*)(Kb + kbase[ks] + 8192); }
;             __builtin_amdgcn_sched_barrier(0);
; #pragma unroll
;             for (int ks = 0; ks < 4; ++ks) {
;                 s0 = __builtin_amdgcn_mfma_f32_32x32x16_bf16(ka[ks][0], qf[ks], s0, 0, 0, 0);
;                 s1 = __builtin_amdgcn_mfma_f32_32x32x16_bf16(ka[ks][1], qf[ks], s1, 0, 0, 0);
;             }
;             if (kb + 63 > qw0) {
; #pragma unroll
;                 for (int j = 0; j < 16; ++j) { const int key = kb + crow(j, hi); if (key > qrow) s0[j] = -INFINITY; if (key + 32 > qrow) s1[j] = -INFINITY; }
;             }
;             float mxa = max3f(s0[0], s1[0], s0[1]), mxb = max3f(s1[1], s0[2], s1[2]), mxc = max3f(s0[3], s1[3], s0[4]), mxd = max3f(s1[4], s0[5], s1[5]);
;             mxa = max3f(mxa, s0[6], s1[6]); mxb = max3f(mxb, s0[7], s1[7]); mxc = max3f(mxc, s0[8], s1[8]); mxd = max3f(mxd, s0[9], s1[9]);
;             mxa = max3f(mxa, s0[10], s1[10]); mxb = max3f(mxb, s0[11], s1[11]); mxc = max3f(mxc, s0[12], s1[12]); mxd = max3f(mxd, s0[13], s1[13]);
;             mxa = max3f(mxa, s0[14], s1[14]); mxb = max3f(mxb, s0[15], s1[15]);
;             float mx = max3f(mxa, mxb, max3f(mxc, mxd, mxd));
;             { auto rr = __builtin_amdgcn_permlane32_swap(__builtin_bit_cast(unsigned, mx), __builtin_bit_cast(unsigned, mx), false, false);
;               mx = fmaxf(__builtin_bit_cast(float, rr[0]), __builtin_bit_cast(float, rr[1])); }
;             if (__any(mx > mrun + 8.0f)) {
	s_waitcnt lgkmcnt(6)
	v_mfma_f32_32x32x16_bf16 v[82:97], v[136:139], v[110:113], v[222:237]
	v_mfma_f32_32x32x16_bf16 v[66:81], v[140:143], v[110:113], v[222:237]
	s_waitcnt lgkmcnt(4)
	v_mfma_f32_32x32x16_bf16 v[82:97], v[204:207], v[106:109], v[82:97]
	v_mfma_f32_32x32x16_bf16 v[66:81], v[208:211], v[106:109], v[66:81]
	s_waitcnt lgkmcnt(2)
	v_mfma_f32_32x32x16_bf16 v[82:97], v[238:241], v[102:105], v[82:97]
	v_mfma_f32_32x32x16_bf16 v[66:81], v[242:245], v[102:105], v[66:81]
	s_waitcnt lgkmcnt(0)
	v_mfma_f32_32x32x16_bf16 v[82:97], v[246:249], v[98:101], v[82:97]
	v_mfma_f32_32x32x16_bf16 v[66:81], v[250:253], v[98:101], v[66:81]
	s_add_i32 m0, s62, 0x0
	s_nop 0
	global_load_lds_dwordx4 v[134:135], off
	s_add_i32 m0, s62, 0x2000
	s_nop 0
	global_load_lds_dwordx4 v[200:201], off
	ds_read_b64_tr_b16 v[136:137], v168 offset:49152
	ds_read_b64_tr_b16 v[138:139], v175 offset:49152
	ds_read_b64_tr_b16 v[140:141], v172 offset:49152
	ds_read_b64_tr_b16 v[142:143], v174 offset:49152
	ds_read_b64_tr_b16 v[204:205], v170 offset:49152
	ds_read_b64_tr_b16 v[206:207], v173 offset:49152
	ds_read_b64_tr_b16 v[208:209], v169 offset:49152
	ds_read_b64_tr_b16 v[210:211], v171 offset:49152
	ds_read_b64_tr_b16 v[238:239], v168 offset:53248
	ds_read_b64_tr_b16 v[240:241], v175 offset:53248
	ds_read_b64_tr_b16 v[242:243], v172 offset:53248
	ds_read_b64_tr_b16 v[244:245], v174 offset:53248
	v_max3_f32 v122, v82, v66, v83
	v_max3_f32 v123, v67, v84, v68
	v_max3_f32 v124, v85, v69, v86
	v_max3_f32 v125, v70, v87, v71
	v_max3_f32 v122, v122, v88, v72
	v_max3_f32 v123, v123, v89, v73
	v_max3_f32 v124, v124, v90, v74
	v_max3_f32 v125, v125, v91, v75
	v_max3_f32 v122, v122, v92, v76
	v_max3_f32 v123, v123, v93, v77
	v_max3_f32 v124, v124, v94, v78
	v_max3_f32 v125, v125, v95, v79
	v_max3_f32 v122, v122, v96, v80
	v_max3_f32 v123, v123, v97, v81
	v_max3_f32 v122, v122, v123, v124
	v_max_f32_e32 v122, v122, v125
	v_mov_b32_e32 v203, v122
	s_nop 1
	v_permlane32_swap_b32_e32 v122, v203
	s_nop 1
	v_max_f32_e32 v122, v122, v203
	s_mov_b32 s39, 0
	v_cmp_lt_f32_e32 vcc, 0x41000000, v122
	s_cmp_eq_u32 s50, 0
	s_cbranch_scc1 .Lat2_u1_first
	s_cbranch_vccz .Lat2_u1_norescale
	s_branch .Lat2_u1_rescale

; #define LAS __attribute__((address_space(3)))
; __device__ __forceinline__ unsigned pk2(float lo, float hi) { f32x2 v = {lo, hi}; bf16x2_t b = __builtin_convertvector(v, bf16x2_t); return __builtin_bit_cast(unsigned, b); }
; __device__ __forceinline__ s16x4 vtr(LAS const unsigned char* p) { return __builtin_bit_cast(s16x4, __builtin_amdgcn_ds_read_tr16_b64_v4i16((LAS v4i16_t*)p)); }
; __device__ __forceinline__ bf16x8 cat8(s16x4 a, s16x4 b) { return (bf16x8){a[0], a[1], a[2], a[3], b[0], b[1], b[2], b[3]}; }
; __device__ __forceinline__ void attn_block(LAS unsigned char* lds, const bf16_t* P, bf16_t* mix, int b, int h, int qb, float lam, float outscale, const float* subln) {
;     ...
;             for (int ks = 0; ks < 4; ++ks) { ka[ks][0] = *(const LAS bf16x8*)(Kb + kbase[ks]); ka[ks][1] = *(const LAS bf16x8*)(Kb + kbase[ks] + 8192); }
;     ...
; #pragma unroll
;             for (int j = 0; j < 16; ++j) { s0[j] = __builtin_amdgcn_exp2f(s0[j] - mrun); s1[j] = __builtin_amdgcn_exp2f(s1[j] - mrun); }
;             float ps0 = 0.f, ps1 = 0.f, ps2 = 0.f, ps3 = 0.f;
; #pragma unroll
;             for (int j = 0; j < 16; j += 2) { ps0 += s0[j]; ps1 += s1[j]; ps2 += s0[j + 1]; ps3 += s1[j + 1]; }
;             lrun += (ps0 + ps1) + (ps2 + ps3);
;             bf16x8 pb[4];
; #pragma unroll
;             for (int s2 = 0; s2 < 2; ++s2) {
;                 u32x4 w0, w1;
;                 w0.x = pk2(s0[8 * s2 + 0], s0[8 * s2 + 1]); w0.y = pk2(s0[8 * s2 + 2], s0[8 * s2 + 3]); w0.z = pk2(s0[8 * s2 + 4], s0[8 * s2 + 5]); w0.w = pk2(s0[8 * s2 + 6], s0[8 * s2 + 7]);
;                 w1.x = pk2(s1[8 * s2 + 0], s1[8 * s2 + 1]); w1.y = pk2(s1[8 * s2 + 2], s1[8 * s2 + 3]); w1.z = pk2(s1[8 * s2 + 4], s1[8 * s2 + 5]); w1.w = pk2(s1[8 * s2 + 6], s1[8 * s2 + 7]);
;                 pb[s2] = __builtin_bit_cast(bf16x8, w0); pb[2 + s2] = __builtin_bit_cast(bf16x8, w1);
;             }
; #pragma unroll
;             for (int s = 0; s < 4; ++s) {
; #pragma unroll
;                 for (int c = 0; c < 4; ++c) {
;                     const s16x4 v0 = vtr(Vb + vbase[c][0] + 4096 * s);
;                     const s16x4 v1 = vtr(Vb + vbase[c][1] + 4096 * s);
;                     o[c] = __builtin_amdgcn_mfma_f32_32x32x16_bf16(cat8(v0, v1), pb[s], o[c], 0, 0, 0);
;                 }
;             }
.Lat2_u1_norescale:
	v_exp_f32_e32 v82, v82
	v_exp_f32_e32 v83, v83
	v_exp_f32_e32 v84, v84
	v_exp_f32_e32 v85, v85
	v_exp_f32_e32 v86, v86
	v_exp_f32_e32 v87, v87
	v_exp_f32_e32 v88, v88
	v_exp_f32_e32 v89, v89
	v_exp_f32_e32 v90, v90
	v_exp_f32_e32 v91, v91
	v_exp_f32_e32 v92, v92
	v_exp_f32_e32 v93, v93
	v_exp_f32_e32 v94, v94
	v_exp_f32_e32 v95, v95
	v_exp_f32_e32 v96, v96
	v_exp_f32_e32 v97, v97
	v_cvt_pk_bf16_f32 v184, v82, v83
	v_cvt_pk_bf16_f32 v185, v84, v85
	v_cvt_pk_bf16_f32 v186, v86, v87
	v_cvt_pk_bf16_f32 v187, v88, v89
	v_cvt_pk_bf16_f32 v188, v90, v91
	v_cvt_pk_bf16_f32 v189, v92, v93
	v_cvt_pk_bf16_f32 v190, v94, v95
	v_cvt_pk_bf16_f32 v191, v96, v97
	v_add_f32_e32 v122, v82, v83
	v_add_f32_e32 v123, v84, v85
	v_add_f32_e32 v122, v122, v86
	v_add_f32_e32 v123, v123, v87
	v_add_f32_e32 v122, v122, v88
	v_add_f32_e32 v123, v123, v89
	v_add_f32_e32 v122, v122, v123
	v_add_f32_e32 v167, v167, v122
	v_add_f32_e32 v124, v90, v91
	v_add_f32_e32 v125, v92, v93
	v_add_f32_e32 v124, v124, v94
	v_add_f32_e32 v125, v125, v95
	v_add_f32_e32 v124, v124, v96
	v_add_f32_e32 v125, v125, v97
	v_add_f32_e32 v124, v124, v125
	v_add_f32_e32 v167, v167, v124
	s_waitcnt lgkmcnt(8)
	v_mfma_f32_32x32x16_bf16 v[50:65], v[136:139], v[184:187], v[50:65]
	ds_read_b64_tr_b16 v[246:247], v170 offset:53248
	ds_read_b64_tr_b16 v[248:249], v173 offset:53248
	v_exp_f32_e32 v66, v66
	v_exp_f32_e32 v67, v67
	v_exp_f32_e32 v68, v68
	v_mfma_f32_32x32x16_bf16 v[34:49], v[140:143], v[184:187], v[34:49]
	ds_read_b64_tr_b16 v[250:251], v169 offset:53248
	ds_read_b64_tr_b16 v[252:253], v171 offset:53248
	v_exp_f32_e32 v69, v69
	v_exp_f32_e32 v70, v70
	v_exp_f32_e32 v71, v71
	s_add_i32 m0, s62, 0x7800
	s_nop 0
	global_load_lds_dwordx4 v[134:135], off offset:2048
	s_waitcnt lgkmcnt(8)
	v_mfma_f32_32x32x16_bf16 v[18:33], v[204:207], v[184:187], v[18:33]
	ds_read_b64_tr_b16 v[136:137], v168 offset:57344
	ds_read_b64_tr_b16 v[138:139], v175 offset:57344
	v_exp_f32_e32 v72, v72
	v_exp_f32_e32 v73, v73
	v_cvt_pk_bf16_f32 v192, v66, v67
	v_mfma_f32_32x32x16_bf16 v[2:17], v[208:211], v[184:187], v[2:17]
	ds_read_b64_tr_b16 v[140:141], v172 offset:57344
	ds_read_b64_tr_b16 v[142:143], v174 offset:57344
	v_cvt_pk_bf16_f32 v193, v68, v69
	v_cvt_pk_bf16_f32 v194, v70, v71
	v_cvt_pk_bf16_f32 v195, v72, v73
	s_add_i32 m0, s62, 0x9800
	s_nop 0
	global_load_lds_dwordx4 v[200:201], off offset:2048
	v_lshl_add_u64 v[134:135], v[134:135], 0, s[40:41]
	v_lshl_add_u64 v[200:201], v[200:201], 0, s[40:41]
	s_waitcnt lgkmcnt(8)
	v_mfma_f32_32x32x16_bf16 v[50:65], v[238:241], v[188:191], v[50:65]
	ds_read_b64_tr_b16 v[204:205], v170 offset:57344
	ds_read_b64_tr_b16 v[206:207], v173 offset:57344
	v_exp_f32_e32 v74, v74
	v_exp_f32_e32 v75, v75
	v_exp_f32_e32 v76, v76
	v_mfma_f32_32x32x16_bf16 v[34:49], v[242:245], v[188:191], v[34:49]
	ds_read_b64_tr_b16 v[208:209], v169 offset:57344
	ds_read_b64_tr_b16 v[210:211], v171 offset:57344
	v_exp_f32_e32 v77, v77
	v_exp_f32_e32 v78, v78
	v_exp_f32_e32 v79, v79
	s_waitcnt lgkmcnt(8)
	v_mfma_f32_32x32x16_bf16 v[18:33], v[246:249], v[188:191], v[18:33]
	ds_read_b64_tr_b16 v[238:239], v168 offset:61440
	ds_read_b64_tr_b16 v[240:241], v175 offset:61440
	v_exp_f32_e32 v80, v80
	v_exp_f32_e32 v81, v81
	v_cvt_pk_bf16_f32 v196, v74, v75
	v_mfma_f32_32x32x16_bf16 v[2:17], v[250:253], v[188:191], v[2:17]
	ds_read_b64_tr_b16 v[242:243], v172 offset:61440
	ds_read_b64_tr_b16 v[244:245], v174 offset:61440
	v_cvt_pk_bf16_f32 v197, v76, v77
	v_cvt_pk_bf16_f32 v198, v78, v79
	v_cvt_pk_bf16_f32 v199, v80, v81
	s_waitcnt lgkmcnt(8)
	v_mfma_f32_32x32x16_bf16 v[50:65], v[136:139], v[192:195], v[50:65]
	ds_read_b64_tr_b16 v[246:247], v170 offset:61440
	ds_read_b64_tr_b16 v[248:249], v173 offset:61440
	v_add_f32_e32 v0, v66, v67
	v_add_f32_e32 v203, v68, v69
	v_add_f32_e32 v0, v0, v70
	v_mfma_f32_32x32x16_bf16 v[34:49], v[140:143], v[192:195], v[34:49]
	ds_read_b64_tr_b16 v[250:251], v169 offset:61440
	ds_read_b64_tr_b16 v[252:253], v171 offset:61440
	v_add_f32_e32 v203, v203, v71
	v_add_f32_e32 v0, v0, v72
	v_add_f32_e32 v203, v203, v73
	s_waitcnt lgkmcnt(8)
	v_mfma_f32_32x32x16_bf16 v[18:33], v[204:207], v[192:195], v[18:33]
	v_add_f32_e32 v0, v0, v203
	v_add_f32_e32 v167, v167, v0
	v_add_f32_e32 v0, v74, v75
	ds_read_b128 v[136:139], v126 offset:0
	ds_read_b128 v[140:143], v126 offset:8192
	v_mfma_f32_32x32x16_bf16 v[2:17], v[208:211], v[192:195], v[2:17]
	v_add_f32_e32 v203, v76, v77
	v_add_f32_e32 v0, v0, v78
	v_add_f32_e32 v203, v203, v79
	ds_read_b128 v[204:207], v127 offset:0
	ds_read_b128 v[208:211], v127 offset:8192
	s_waitcnt lgkmcnt(8)
	v_mfma_f32_32x32x16_bf16 v[50:65], v[238:241], v[196:199], v[50:65]
	v_add_f32_e32 v0, v0, v80
	v_add_f32_e32 v203, v203, v81
	v_add_f32_e32 v0, v0, v203
	v_mfma_f32_32x32x16_bf16 v[34:49], v[242:245], v[196:199], v[34:49]
	v_add_f32_e32 v167, v167, v0
	ds_read_b128 v[238:241], v128 offset:0
	ds_read_b128 v[242:245], v128 offset:8192
	s_waitcnt lgkmcnt(6)
	v_mfma_f32_32x32x16_bf16 v[18:33], v[246:249], v[196:199], v[18:33]
	v_mfma_f32_32x32x16_bf16 v[2:17], v[250:253], v[196:199], v[2:17]
	ds_read_b128 v[246:249], v129 offset:0
	ds_read_b128 v[250:253], v129 offset:8192
	s_waitcnt vmcnt(6)
	s_add_i32 s50, s50, 64
	s_barrier
; #define LAS __attribute__((address_space(3)))
; __device__ __forceinline__ float max3f(float a, float b, float c) { float r; asm("v_max3_f32 %0, %1, %2, %3" : "=v"(r) : "v"(a), "v"(b), "v"(c)); return r; }
; __device__ __forceinline__ void attn_block(LAS unsigned char* lds, const bf16_t* P, bf16_t* mix, int b, int h, int qb, float lam, float outscale, const float* subln) {
;     ...
;         const int kb = 64 * kt;
;         if (kb <= qw0 + 31) {
;             LAS const unsigned char* Kb = lds + ATT_K0 + buf * 16384;
;             LAS const unsigned char* Vb = lds + ATT_V0 + buf * 16384;
;             f32x16 s0, s1;
; #pragma unroll
;             for (int j = 0; j < 16; ++j) { s0[j] = 0.f; s1[j] = 0.f; }
;             bf16x8 ka[4][2];
; #pragma unroll
;             for (int ks = 0; ks < 4; ++ks) { ka[ks][0] = *(const LAS bf16x8*)(Kb + kbase[ks]); ka[ks][1] = *(const LAS bf16x8*)(Kb + kbase[ks] + 8192); }
;             __builtin_amdgcn_sched_barrier(0);
; #pragma unroll
;             for (int ks = 0; ks < 4; ++ks) {
;                 s0 = __builtin_amdgcn_mfma_f32_32x32x16_bf16(ka[ks][0], qf[ks], s0, 0, 0, 0);
;                 s1 = __builtin_amdgcn_mfma_f32_32x32x16_bf16(ka[ks][1], qf[ks], s1, 0, 0, 0);
;             }
;             if (kb + 63 > qw0) {
; #pragma unroll
;                 for (int j = 0; j < 16; ++j) { const int key = kb + crow(j, hi); if (key > qrow) s0[j] = -INFINITY; if (key + 32 > qrow) s1[j] = -INFINITY; }
;             }
;             float mxa = max3f(s0[0], s1[0], s0[1]), mxb = max3f(s1[1], s0[2], s1[2]), mxc = max3f(s0[3], s1[3], s0[4]), mxd = max3f(s1[4], s0[5], s1[5]);
;             mxa = max3f(mxa, s0[6], s1[6]); mxb = max3f(mxb, s0[7], s1[7]); mxc = max3f(mxc, s0[8], s1[8]); mxd = max3f(mxd, s0[9], s1[9]);
;             mxa = max3f(mxa, s0[10], s1[10]); mxb = max3f(mxb, s0[11], s1[11]); mxc = max3f(mxc, s0[12], s1[12]); mxd = max3f(mxd, s0[13], s1[13]);
;             mxa = max3f(mxa, s0[14], s1[14]); mxb = max3f(mxb, s0[15], s1[15]);
;             float mx = max3f(mxa, mxb, max3f(mxc, mxd, mxd));
;             { auto rr = __builtin_amdgcn_permlane32_swap(__builtin_bit_cast(unsigned, mx), __builtin_bit_cast(unsigned, mx), false, false);
;               mx = fmaxf(__builtin_bit_cast(float, rr[0]), __builtin_bit_cast(float, rr[1])); }
;             if (__any(mx > mrun + 8.0f)) {
	s_waitcnt lgkmcnt(6)
	v_mfma_f32_32x32x16_bf16 v[82:97], v[136:139], v[110:113], v[222:237]
	v_mfma_f32_32x32x16_bf16 v[66:81], v[140:143], v[110:113], v[222:237]
	s_waitcnt lgkmcnt(4)
	v_mfma_f32_32x32x16_bf16 v[82:97], v[204:207], v[106:109], v[82:97]
	v_mfma_f32_32x32x16_bf16 v[66:81], v[208:211], v[106:109], v[66:81]
	s_waitcnt lgkmcnt(2)
	v_mfma_f32_32x32x16_bf16 v[82:97], v[238:241], v[102:105], v[82:97]
	v_mfma_f32_32x32x16_bf16 v[66:81], v[242:245], v[102:105], v[66:81]
	s_waitcnt lgkmcnt(0)
	v_mfma_f32_32x32x16_bf16 v[82:97], v[246:249], v[98:101], v[82:97]
	v_mfma_f32_32x32x16_bf16 v[66:81], v[250:253], v[98:101], v[66:81]
	s_add_i32 m0, s62, 0x4000
	s_nop 0
	global_load_lds_dwordx4 v[134:135], off
	s_add_i32 m0, s62, 0x6000
	s_nop 0
	global_load_lds_dwordx4 v[200:201], off
	ds_read_b64_tr_b16 v[136:137], v114 offset:32768
	ds_read_b64_tr_b16 v[138:139], v115 offset:32768
	ds_read_b64_tr_b16 v[140:141], v116 offset:32768
	ds_read_b64_tr_b16 v[142:143], v117 offset:32768
	ds_read_b64_tr_b16 v[204:205], v118 offset:32768
	ds_read_b64_tr_b16 v[206:207], v119 offset:32768
	ds_read_b64_tr_b16 v[208:209], v120 offset:32768
	ds_read_b64_tr_b16 v[210:211], v121 offset:32768
	ds_read_b64_tr_b16 v[238:239], v114 offset:36864
	ds_read_b64_tr_b16 v[240:241], v115 offset:36864
	ds_read_b64_tr_b16 v[242:243], v116 offset:36864
	ds_read_b64_tr_b16 v[244:245], v117 offset:36864
	v_max3_f32 v122, v82, v66, v83
	v_max3_f32 v123, v67, v84, v68
	v_max3_f32 v124, v85, v69, v86
	v_max3_f32 v125, v70, v87, v71
	v_max3_f32 v122, v122, v88, v72
	v_max3_f32 v123, v123, v89, v73
	v_max3_f32 v124, v124, v90, v74
	v_max3_f32 v125, v125, v91, v75
	v_max3_f32 v122, v122, v92, v76
	v_max3_f32 v123, v123, v93, v77
	v_max3_f32 v124, v124, v94, v78
	v_max3_f32 v125, v125, v95, v79
	v_max3_f32 v122, v122, v96, v80
	v_max3_f32 v123, v123, v97, v81
	v_max3_f32 v122, v122, v123, v124
	v_max_f32_e32 v122, v122, v125
	v_mov_b32_e32 v203, v122
	s_nop 1
	v_permlane32_swap_b32_e32 v122, v203
	s_nop 1
	v_max_f32_e32 v122, v122, v203
	s_mov_b32 s39, 0
	v_cmp_lt_f32_e32 vcc, 0x41000000, v122
	s_cmp_eq_u32 s50, 0
	s_cbranch_scc1 .Lat2_u2_first
	s_cbranch_vccz .Lat2_u2_norescale
	s_branch .Lat2_u2_rescale

; #define LAS __attribute__((address_space(3)))
; __device__ __forceinline__ unsigned pk2(float lo, float hi) { f32x2 v = {lo, hi}; bf16x2_t b = __builtin_convertvector(v, bf16x2_t); return __builtin_bit_cast(unsigned, b); }
; __device__ __forceinline__ s16x4 vtr(LAS const unsigned char* p) { return __builtin_bit_cast(s16x4, __builtin_amdgcn_ds_read_tr16_b64_v4i16((LAS v4i16_t*)p)); }
; __device__ __forceinline__ bf16x8 cat8(s16x4 a, s16x4 b) { return (bf16x8){a[0], a[1], a[2], a[3], b[0], b[1], b[2], b[3]}; }
; __device__ __forceinline__ void attn_block(LAS unsigned char* lds, const bf16_t* P, bf16_t* mix, int b, int h, int qb, float lam, float outscale, const float* subln) {
;     ...
;             for (int ks = 0; ks < 4; ++ks) { ka[ks][0] = *(const LAS bf16x8*)(Kb + kbase[ks]); ka[ks][1] = *(const LAS bf16x8*)(Kb + kbase[ks] + 8192); }
;     ...
; #pragma unroll
;             for (int j = 0; j < 16; ++j) { s0[j] = __builtin_amdgcn_exp2f(s0[j] - mrun); s1[j] = __builtin_amdgcn_exp2f(s1[j] - mrun); }
;             float ps0 = 0.f, ps1 = 0.f, ps2 = 0.f, ps3 = 0.f;
; #pragma unroll
;             for (int j = 0; j < 16; j += 2) { ps0 += s0[j]; ps1 += s1[j]; ps2 += s0[j + 1]; ps3 += s1[j + 1]; }
;             lrun += (ps0 + ps1) + (ps2 + ps3);
;             bf16x8 pb[4];
; #pragma unroll
;             for (int s2 = 0; s2 < 2; ++s2) {
;                 u32x4 w0, w1;
;                 w0.x = pk2(s0[8 * s2 + 0], s0[8 * s2 + 1]); w0.y = pk2(s0[8 * s2 + 2], s0[8 * s2 + 3]); w0.z = pk2(s0[8 * s2 + 4], s0[8 * s2 + 5]); w0.w = pk2(s0[8 * s2 + 6], s0[8 * s2 + 7]);
;                 w1.x = pk2(s1[8 * s2 + 0], s1[8 * s2 + 1]); w1.y = pk2(s1[8 * s2 + 2], s1[8 * s2 + 3]); w1.z = pk2(s1[8 * s2 + 4], s1[8 * s2 + 5]); w1.w = pk2(s1[8 * s2 + 6], s1[8 * s2 + 7]);
;                 pb[s2] = __builtin_bit_cast(bf16x8, w0); pb[2 + s2] = __builtin_bit_cast(bf16x8, w1);
;             }
; #pragma unroll
;             for (int s = 0; s < 4; ++s) {
; #pragma unroll
;                 for (int c = 0; c < 4; ++c) {
;                     const s16x4 v0 = vtr(Vb + vbase[c][0] + 4096 * s);
;                     const s16x4 v1 = vtr(Vb + vbase[c][1] + 4096 * s);
;                     o[c] = __builtin_amdgcn_mfma_f32_32x32x16_bf16(cat8(v0, v1), pb[s], o[c], 0, 0, 0);
;                 }
;             }
.Lat2_u2_norescale:
	v_exp_f32_e32 v82, v82
	v_exp_f32_e32 v83, v83
	v_exp_f32_e32 v84, v84
	v_exp_f32_e32 v85, v85
	v_exp_f32_e32 v86, v86
	v_exp_f32_e32 v87, v87
	v_exp_f32_e32 v88, v88
	v_exp_f32_e32 v89, v89
	v_exp_f32_e32 v90, v90
	v_exp_f32_e32 v91, v91
	v_exp_f32_e32 v92, v92
	v_exp_f32_e32 v93, v93
	v_exp_f32_e32 v94, v94
	v_exp_f32_e32 v95, v95
	v_exp_f32_e32 v96, v96
	v_exp_f32_e32 v97, v97
	v_cvt_pk_bf16_f32 v184, v82, v83
	v_cvt_pk_bf16_f32 v185, v84, v85
	v_cvt_pk_bf16_f32 v186, v86, v87
	v_cvt_pk_bf16_f32 v187, v88, v89
	v_cvt_pk_bf16_f32 v188, v90, v91
	v_cvt_pk_bf16_f32 v189, v92, v93
	v_cvt_pk_bf16_f32 v190, v94, v95
	v_cvt_pk_bf16_f32 v191, v96, v97
	v_add_f32_e32 v122, v82, v83
	v_add_f32_e32 v123, v84, v85
	v_add_f32_e32 v122, v122, v86
	v_add_f32_e32 v123, v123, v87
	v_add_f32_e32 v122, v122, v88
	v_add_f32_e32 v123, v123, v89
	v_add_f32_e32 v122, v122, v123
	v_add_f32_e32 v167, v167, v122
	v_add_f32_e32 v124, v90, v91
	v_add_f32_e32 v125, v92, v93
	v_add_f32_e32 v124, v124, v94
	v_add_f32_e32 v125, v125, v95
	v_add_f32_e32 v124, v124, v96
	v_add_f32_e32 v125, v125, v97
	v_add_f32_e32 v124, v124, v125
	v_add_f32_e32 v167, v167, v124
	s_waitcnt lgkmcnt(8)
	v_mfma_f32_32x32x16_bf16 v[50:65], v[136:139], v[184:187], v[50:65]
	ds_read_b64_tr_b16 v[246:247], v118 offset:36864
	ds_read_b64_tr_b16 v[248:249], v119 offset:36864
	v_exp_f32_e32 v66, v66
	v_exp_f32_e32 v67, v67
	v_exp_f32_e32 v68, v68
	v_mfma_f32_32x32x16_bf16 v[34:49], v[140:143], v[184:187], v[34:49]
	ds_read_b64_tr_b16 v[250:251], v120 offset:36864
	ds_read_b64_tr_b16 v[252:253], v121 offset:36864
	v_exp_f32_e32 v69, v69
	v_exp_f32_e32 v70, v70
	v_exp_f32_e32 v71, v71
	s_add_i32 m0, s62, 0xb800
	s_nop 0
	global_load_lds_dwordx4 v[134:135], off offset:2048
	s_waitcnt lgkmcnt(8)
	v_mfma_f32_32x32x16_bf16 v[18:33], v[204:207], v[184:187], v[18:33]
	ds_read_b64_tr_b16 v[136:137], v114 offset:40960
	ds_read_b64_tr_b16 v[138:139], v115 offset:40960
	v_exp_f32_e32 v72, v72
	v_exp_f32_e32 v73, v73
	v_cvt_pk_bf16_f32 v192, v66, v67
	v_mfma_f32_32x32x16_bf16 v[2:17], v[208:211], v[184:187], v[2:17]
	ds_read_b64_tr_b16 v[140:141], v116 offset:40960
	ds_read_b64_tr_b16 v[142:143], v117 offset:40960
	v_cvt_pk_bf16_f32 v193, v68, v69
	v_cvt_pk_bf16_f32 v194, v70, v71
	v_cvt_pk_bf16_f32 v195, v72, v73
	s_add_i32 m0, s62, 0xd800
	s_nop 0
	global_load_lds_dwordx4 v[200:201], off offset:2048
	v_lshl_add_u64 v[134:135], v[134:135], 0, s[40:41]
	v_lshl_add_u64 v[200:201], v[200:201], 0, s[40:41]
	s_waitcnt lgkmcnt(8)
	v_mfma_f32_32x32x16_bf16 v[50:65], v[238:241], v[188:191], v[50:65]
	ds_read_b64_tr_b16 v[204:205], v118 offset:40960
	ds_read_b64_tr_b16 v[206:207], v119 offset:40960
	v_exp_f32_e32 v74, v74
	v_exp_f32_e32 v75, v75
	v_exp_f32_e32 v76, v76
	v_mfma_f32_32x32x16_bf16 v[34:49], v[242:245], v[188:191], v[34:49]
	ds_read_b64_tr_b16 v[208:209], v120 offset:40960
	ds_read_b64_tr_b16 v[210:211], v121 offset:40960
	v_exp_f32_e32 v77, v77
	v_exp_f32_e32 v78, v78
	v_exp_f32_e32 v79, v79
	s_waitcnt lgkmcnt(8)
	v_mfma_f32_32x32x16_bf16 v[18:33], v[246:249], v[188:191], v[18:33]
	ds_read_b64_tr_b16 v[238:239], v114 offset:45056
	ds_read_b64_tr_b16 v[240:241], v115 offset:45056
	v_exp_f32_e32 v80, v80
	v_exp_f32_e32 v81, v81
	v_cvt_pk_bf16_f32 v196, v74, v75
	v_mfma_f32_32x32x16_bf16 v[2:17], v[250:253], v[188:191], v[2:17]
	ds_read_b64_tr_b16 v[242:243], v116 offset:45056
	ds_read_b64_tr_b16 v[244:245], v117 offset:45056
	v_cvt_pk_bf16_f32 v197, v76, v77
	v_cvt_pk_bf16_f32 v198, v78, v79
	v_cvt_pk_bf16_f32 v199, v80, v81
	s_waitcnt lgkmcnt(8)
	v_mfma_f32_32x32x16_bf16 v[50:65], v[136:139], v[192:195], v[50:65]
	ds_read_b64_tr_b16 v[246:247], v118 offset:45056
	ds_read_b64_tr_b16 v[248:249], v119 offset:45056
	v_add_f32_e32 v0, v66, v67
	v_add_f32_e32 v203, v68, v69
	v_add_f32_e32 v0, v0, v70
	v_mfma_f32_32x32x16_bf16 v[34:49], v[140:143], v[192:195], v[34:49]
	ds_read_b64_tr_b16 v[250:251], v120 offset:45056
	ds_read_b64_tr_b16 v[252:253], v121 offset:45056
	v_add_f32_e32 v203, v203, v71
	v_add_f32_e32 v0, v0, v72
	v_add_f32_e32 v203, v203, v73
	s_waitcnt lgkmcnt(8)
	v_mfma_f32_32x32x16_bf16 v[18:33], v[204:207], v[192:195], v[18:33]
	v_add_f32_e32 v0, v0, v203
	v_add_f32_e32 v167, v167, v0
	v_add_f32_e32 v0, v74, v75
	ds_read_b128 v[136:139], v126 offset:16384
	ds_read_b128 v[140:143], v126 offset:24576
	v_mfma_f32_32x32x16_bf16 v[2:17], v[208:211], v[192:195], v[2:17]
	v_add_f32_e32 v203, v76, v77
	v_add_f32_e32 v0, v0, v78
	v_add_f32_e32 v203, v203, v79
	ds_read_b128 v[204:207], v127 offset:16384
	ds_read_b128 v[208:211], v127 offset:24576
	s_waitcnt lgkmcnt(8)
	v_mfma_f32_32x32x16_bf16 v[50:65], v[238:241], v[196:199], v[50:65]
	v_add_f32_e32 v0, v0, v80
	v_add_f32_e32 v203, v203, v81
	v_add_f32_e32 v0, v0, v203
	v_mfma_f32_32x32x16_bf16 v[34:49], v[242:245], v[196:199], v[34:49]
	v_add_f32_e32 v167, v167, v0
	ds_read_b128 v[238:241], v128 offset:16384
	ds_read_b128 v[242:245], v128 offset:24576
	s_waitcnt lgkmcnt(6)
	v_mfma_f32_32x32x16_bf16 v[18:33], v[246:249], v[196:199], v[18:33]
	v_mfma_f32_32x32x16_bf16 v[2:17], v[250:253], v[196:199], v[2:17]
	ds_read_b128 v[246:249], v129 offset:16384
	ds_read_b128 v[250:253], v129 offset:24576
	s_waitcnt vmcnt(6)
	s_add_i32 s50, s50, 64
	s_barrier
; #define LAS __attribute__((address_space(3)))
; __device__ __forceinline__ float max3f(float a, float b, float c) { float r; asm("v_max3_f32 %0, %1, %2, %3" : "=v"(r) : "v"(a), "v"(b), "v"(c)); return r; }
; __device__ __forceinline__ void attn_block(LAS unsigned char* lds, const bf16_t* P, bf16_t* mix, int b, int h, int qb, float lam, float outscale, const float* subln) {
;     ...
;         const int kb = 64 * kt;
;         if (kb <= qw0 + 31) {
;             LAS const unsigned char* Kb = lds + ATT_K0 + buf * 16384;
;             LAS const unsigned char* Vb = lds + ATT_V0 + buf * 16384;
;             f32x16 s0, s1;
; #pragma unroll
;             for (int j = 0; j < 16; ++j) { s0[j] = 0.f; s1[j] = 0.f; }
;             bf16x8 ka[4][2];
; #pragma unroll
;             for (int ks = 0; ks < 4; ++ks) { ka[ks][0] = *(const LAS bf16x8*)(Kb + kbase[ks]); ka[ks][1] = *(const LAS bf16x8*)(Kb + kbase[ks] + 8192); }
;             __builtin_amdgcn_sched_barrier(0);
; #pragma unroll
;             for (int ks = 0; ks < 4; ++ks) {
;                 s0 = __builtin_amdgcn_mfma_f32_32x32x16_bf16(ka[ks][0], qf[ks], s0, 0, 0, 0);
;                 s1 = __builtin_amdgcn_mfma_f32_32x32x16_bf16(ka[ks][1], qf[ks], s1, 0, 0, 0);
;             }
;             if (kb + 63 > qw0) {
; #pragma unroll
;                 for (int j = 0; j < 16; ++j) { const int key = kb + crow(j, hi); if (key > qrow) s0[j] = -INFINITY; if (key + 32 > qrow) s1[j] = -INFINITY; }
;             }
;             float mxa = max3f(s0[0], s1[0], s0[1]), mxb = max3f(s1[1], s0[2], s1[2]), mxc = max3f(s0[3], s1[3], s0[4]), mxd = max3f(s1[4], s0[5], s1[5]);
;             mxa = max3f(mxa, s0[6], s1[6]); mxb = max3f(mxb, s0[7], s1[7]); mxc = max3f(mxc, s0[8], s1[8]); mxd = max3f(mxd, s0[9], s1[9]);
;             mxa = max3f(mxa, s0[10], s1[10]); mxb = max3f(mxb, s0[11], s1[11]); mxc = max3f(mxc, s0[12], s1[12]); mxd = max3f(mxd, s0[13], s1[13]);
;             mxa = max3f(mxa, s0[14], s1[14]); mxb = max3f(mxb, s0[15], s1[15]);
;             float mx = max3f(mxa, mxb, max3f(mxc, mxd, mxd));
;             { auto rr = __builtin_amdgcn_permlane32_swap(__builtin_bit_cast(unsigned, mx), __builtin_bit_cast(unsigned, mx), false, false);
;               mx = fmaxf(__builtin_bit_cast(float, rr[0]), __builtin_bit_cast(float, rr[1])); }
;             if (__any(mx > mrun + 8.0f)) {
	s_waitcnt lgkmcnt(6)
	v_mfma_f32_32x32x16_bf16 v[82:97], v[136:139], v[110:113], v[222:237]
	v_mfma_f32_32x32x16_bf16 v[66:81], v[140:143], v[110:113], v[222:237]
	s_waitcnt lgkmcnt(4)
	v_mfma_f32_32x32x16_bf16 v[82:97], v[204:207], v[106:109], v[82:97]
	v_mfma_f32_32x32x16_bf16 v[66:81], v[208:211], v[106:109], v[66:81]
	s_waitcnt lgkmcnt(2)
	v_mfma_f32_32x32x16_bf16 v[82:97], v[238:241], v[102:105], v[82:97]
	v_mfma_f32_32x32x16_bf16 v[66:81], v[242:245], v[102:105], v[66:81]
	s_waitcnt lgkmcnt(0)
	v_mfma_f32_32x32x16_bf16 v[82:97], v[246:249], v[98:101], v[82:97]
	v_mfma_f32_32x32x16_bf16 v[66:81], v[250:253], v[98:101], v[66:81]
	s_add_i32 m0, s62, 0x10000
	s_nop 0
	global_load_lds_dwordx4 v[134:135], off
	s_add_i32 m0, s62, 0x12000
	s_nop 0
	global_load_lds_dwordx4 v[200:201], off
	ds_read_b64_tr_b16 v[136:137], v114 offset:49152
	ds_read_b64_tr_b16 v[138:139], v115 offset:49152
	ds_read_b64_tr_b16 v[140:141], v116 offset:49152
	ds_read_b64_tr_b16 v[142:143], v117 offset:49152
	ds_read_b64_tr_b16 v[204:205], v118 offset:49152
	ds_read_b64_tr_b16 v[206:207], v119 offset:49152
	ds_read_b64_tr_b16 v[208:209], v120 offset:49152
	ds_read_b64_tr_b16 v[210:211], v121 offset:49152
	ds_read_b64_tr_b16 v[238:239], v114 offset:53248
	ds_read_b64_tr_b16 v[240:241], v115 offset:53248
	ds_read_b64_tr_b16 v[242:243], v116 offset:53248
	ds_read_b64_tr_b16 v[244:245], v117 offset:53248
	v_max3_f32 v122, v82, v66, v83
	v_max3_f32 v123, v67, v84, v68
	v_max3_f32 v124, v85, v69, v86
	v_max3_f32 v125, v70, v87, v71
	v_max3_f32 v122, v122, v88, v72
	v_max3_f32 v123, v123, v89, v73
	v_max3_f32 v124, v124, v90, v74
	v_max3_f32 v125, v125, v91, v75
	v_max3_f32 v122, v122, v92, v76
	v_max3_f32 v123, v123, v93, v77
	v_max3_f32 v124, v124, v94, v78
	v_max3_f32 v125, v125, v95, v79
	v_max3_f32 v122, v122, v96, v80
	v_max3_f32 v123, v123, v97, v81
	v_max3_f32 v122, v122, v123, v124
	v_max_f32_e32 v122, v122, v125
	v_mov_b32_e32 v203, v122
	s_nop 1
	v_permlane32_swap_b32_e32 v122, v203
	s_nop 1
	v_max_f32_e32 v122, v122, v203
	s_mov_b32 s39, 0
	v_cmp_lt_f32_e32 vcc, 0x41000000, v122
	s_cmp_eq_u32 s50, 0
	s_cbranch_scc1 .Lat2_u3_first
	s_cbranch_vccz .Lat2_u3_norescale
	s_branch .Lat2_u3_rescale

; __device__ __forceinline__ unsigned pk2(float lo, float hi) { f32x2 v = {lo, hi}; bf16x2_t b = __builtin_convertvector(v, bf16x2_t); return __builtin_bit_cast(unsigned, b); }
; __device__ __forceinline__ s16x4 vtr(LAS const unsigned char* p) { return __builtin_bit_cast(s16x4, __builtin_amdgcn_ds_read_tr16_b64_v4i16((LAS v4i16_t*)p)); }
; __device__ __forceinline__ bf16x8 cat8(s16x4 a, s16x4 b) { return (bf16x8){a[0], a[1], a[2], a[3], b[0], b[1], b[2], b[3]}; }
; __device__ __forceinline__ void attn_block(LAS unsigned char* lds, const bf16_t* P, bf16_t* mix, int b, int h, int qb, float lam, float outscale, const float* subln) {
;     ...
;     for (int kt = 0; kt < ntiles; ++kt) {
;     ...
; #pragma unroll
;             for (int j = 0; j < 16; ++j) { s0[j] = __builtin_amdgcn_exp2f(s0[j] - mrun); s1[j] = __builtin_amdgcn_exp2f(s1[j] - mrun); }
;             float ps0 = 0.f, ps1 = 0.f, ps2 = 0.f, ps3 = 0.f;
; #pragma unroll
;             for (int j = 0; j < 16; j += 2) { ps0 += s0[j]; ps1 += s1[j]; ps2 += s0[j + 1]; ps3 += s1[j + 1]; }
;             lrun += (ps0 + ps1) + (ps2 + ps3);
;             bf16x8 pb[4];
; #pragma unroll
;             for (int s2 = 0; s2 < 2; ++s2) {
;                 u32x4 w0, w1;
;                 w0.x = pk2(s0[8 * s2 + 0], s0[8 * s2 + 1]); w0.y = pk2(s0[8 * s2 + 2], s0[8 * s2 + 3]); w0.z = pk2(s0[8 * s2 + 4], s0[8 * s2 + 5]); w0.w = pk2(s0[8 * s2 + 6], s0[8 * s2 + 7]);
;                 w1.x = pk2(s1[8 * s2 + 0], s1[8 * s2 + 1]); w1.y = pk2(s1[8 * s2 + 2], s1[8 * s2 + 3]); w1.z = pk2(s1[8 * s2 + 4], s1[8 * s2 + 5]); w1.w = pk2(s1[8 * s2 + 6], s1[8 * s2 + 7]);
;                 pb[s2] = __builtin_bit_cast(bf16x8, w0); pb[2 + s2] = __builtin_bit_cast(bf16x8, w1);
;             }
; #pragma unroll
;             for (int s = 0; s < 4; ++s) {
; #pragma unroll
;                 for (int c = 0; c < 4; ++c) {
;                     const s16x4 v0 = vtr(Vb + vbase[c][0] + 4096 * s);
;                     const s16x4 v1 = vtr(Vb + vbase[c][1] + 4096 * s);
;                     o[c] = __builtin_amdgcn_mfma_f32_32x32x16_bf16(cat8(v0, v1), pb[s], o[c], 0, 0, 0);
;                 }
;             }
.Lat2_u3_norescale:
	v_exp_f32_e32 v82, v82
	v_exp_f32_e32 v83, v83
	v_exp_f32_e32 v84, v84
	v_exp_f32_e32 v85, v85
	v_exp_f32_e32 v86, v86
	v_exp_f32_e32 v87, v87
	v_exp_f32_e32 v88, v88
	v_exp_f32_e32 v89, v89
	v_exp_f32_e32 v90, v90
	v_exp_f32_e32 v91, v91
	v_exp_f32_e32 v92, v92
	v_exp_f32_e32 v93, v93
	v_exp_f32_e32 v94, v94
	v_exp_f32_e32 v95, v95
	v_exp_f32_e32 v96, v96
	v_exp_f32_e32 v97, v97
	v_cvt_pk_bf16_f32 v184, v82, v83
	v_cvt_pk_bf16_f32 v185, v84, v85
	v_cvt_pk_bf16_f32 v186, v86, v87
	v_cvt_pk_bf16_f32 v187, v88, v89
	v_cvt_pk_bf16_f32 v188, v90, v91
	v_cvt_pk_bf16_f32 v189, v92, v93
	v_cvt_pk_bf16_f32 v190, v94, v95
	v_cvt_pk_bf16_f32 v191, v96, v97
	v_add_f32_e32 v122, v82, v83
	v_add_f32_e32 v123, v84, v85
	v_add_f32_e32 v122, v122, v86
	v_add_f32_e32 v123, v123, v87
	v_add_f32_e32 v122, v122, v88
	v_add_f32_e32 v123, v123, v89
	v_add_f32_e32 v122, v122, v123
	v_add_f32_e32 v167, v167, v122
	v_add_f32_e32 v124, v90, v91
	v_add_f32_e32 v125, v92, v93
	v_add_f32_e32 v124, v124, v94
	v_add_f32_e32 v125, v125, v95
	v_add_f32_e32 v124, v124, v96
	v_add_f32_e32 v125, v125, v97
	v_add_f32_e32 v124, v124, v125
	v_add_f32_e32 v167, v167, v124
	s_waitcnt lgkmcnt(8)
	v_mfma_f32_32x32x16_bf16 v[50:65], v[136:139], v[184:187], v[50:65]
	ds_read_b64_tr_b16 v[246:247], v118 offset:53248
	ds_read_b64_tr_b16 v[248:249], v119 offset:53248
	v_exp_f32_e32 v66, v66
	v_exp_f32_e32 v67, v67
	v_exp_f32_e32 v68, v68
	v_mfma_f32_32x32x16_bf16 v[34:49], v[140:143], v[184:187], v[34:49]
	ds_read_b64_tr_b16 v[250:251], v120 offset:53248
	ds_read_b64_tr_b16 v[252:253], v121 offset:53248
	v_exp_f32_e32 v69, v69
	v_exp_f32_e32 v70, v70
	v_exp_f32_e32 v71, v71
	s_add_i32 m0, s62, 0x17800
	s_nop 0
	global_load_lds_dwordx4 v[134:135], off offset:2048
	s_waitcnt lgkmcnt(8)
	v_mfma_f32_32x32x16_bf16 v[18:33], v[204:207], v[184:187], v[18:33]
	ds_read_b64_tr_b16 v[136:137], v114 offset:57344
	ds_read_b64_tr_b16 v[138:139], v115 offset:57344
	v_exp_f32_e32 v72, v72
	v_exp_f32_e32 v73, v73
	v_cvt_pk_bf16_f32 v192, v66, v67
	v_mfma_f32_32x32x16_bf16 v[2:17], v[208:211], v[184:187], v[2:17]
	ds_read_b64_tr_b16 v[140:141], v116 offset:57344
	ds_read_b64_tr_b16 v[142:143], v117 offset:57344
	v_cvt_pk_bf16_f32 v193, v68, v69
	v_cvt_pk_bf16_f32 v194, v70, v71
	v_cvt_pk_bf16_f32 v195, v72, v73
	s_add_i32 m0, s62, 0x19800
	s_nop 0
	global_load_lds_dwordx4 v[200:201], off offset:2048
	v_lshl_add_u64 v[134:135], v[134:135], 0, s[40:41]
	v_lshl_add_u64 v[200:201], v[200:201], 0, s[40:41]
	s_waitcnt lgkmcnt(8)
	v_mfma_f32_32x32x16_bf16 v[50:65], v[238:241], v[188:191], v[50:65]
	ds_read_b64_tr_b16 v[204:205], v118 offset:57344
	ds_read_b64_tr_b16 v[206:207], v119 offset:57344
	v_exp_f32_e32 v74, v74
	v_exp_f32_e32 v75, v75
	v_exp_f32_e32 v76, v76
	v_mfma_f32_32x32x16_bf16 v[34:49], v[242:245], v[188:191], v[34:49]
	ds_read_b64_tr_b16 v[208:209], v120 offset:57344
	ds_read_b64_tr_b16 v[210:211], v121 offset:57344
	v_exp_f32_e32 v77, v77
	v_exp_f32_e32 v78, v78
	v_exp_f32_e32 v79, v79
	s_waitcnt lgkmcnt(8)
	v_mfma_f32_32x32x16_bf16 v[18:33], v[246:249], v[188:191], v[18:33]
	ds_read_b64_tr_b16 v[238:239], v114 offset:61440
	ds_read_b64_tr_b16 v[240:241], v115 offset:61440
	v_exp_f32_e32 v80, v80
	v_exp_f32_e32 v81, v81
	v_cvt_pk_bf16_f32 v196, v74, v75
	v_mfma_f32_32x32x16_bf16 v[2:17], v[250:253], v[188:191], v[2:17]
	ds_read_b64_tr_b16 v[242:243], v116 offset:61440
	ds_read_b64_tr_b16 v[244:245], v117 offset:61440
	v_cvt_pk_bf16_f32 v197, v76, v77
	v_cvt_pk_bf16_f32 v198, v78, v79
	v_cvt_pk_bf16_f32 v199, v80, v81
	s_waitcnt lgkmcnt(8)
	v_mfma_f32_32x32x16_bf16 v[50:65], v[136:139], v[192:195], v[50:65]
	ds_read_b64_tr_b16 v[246:247], v118 offset:61440
	ds_read_b64_tr_b16 v[248:249], v119 offset:61440
	v_add_f32_e32 v0, v66, v67
	v_add_f32_e32 v203, v68, v69
	v_add_f32_e32 v0, v0, v70
	v_mfma_f32_32x32x16_bf16 v[34:49], v[140:143], v[192:195], v[34:49]
	ds_read_b64_tr_b16 v[250:251], v120 offset:61440
	ds_read_b64_tr_b16 v[252:253], v121 offset:61440
	v_add_f32_e32 v203, v203, v71
	v_add_f32_e32 v0, v0, v72
	v_add_f32_e32 v203, v203, v73
	s_waitcnt lgkmcnt(8)
	v_mfma_f32_32x32x16_bf16 v[18:33], v[204:207], v[192:195], v[18:33]
	v_add_f32_e32 v0, v0, v203
	v_add_f32_e32 v167, v167, v0
	v_add_f32_e32 v0, v74, v75
	ds_read_b128 v[136:139], v178 offset:0
	ds_read_b128 v[140:143], v178 offset:8192
	v_mfma_f32_32x32x16_bf16 v[2:17], v[208:211], v[192:195], v[2:17]
	v_add_f32_e32 v203, v76, v77
	v_add_f32_e32 v0, v0, v78
	v_add_f32_e32 v203, v203, v79
	ds_read_b128 v[204:207], v181 offset:0
	ds_read_b128 v[208:211], v181 offset:8192
	s_waitcnt lgkmcnt(8)
	v_mfma_f32_32x32x16_bf16 v[50:65], v[238:241], v[196:199], v[50:65]
	v_add_f32_e32 v0, v0, v80
	v_add_f32_e32 v203, v203, v81
	v_add_f32_e32 v0, v0, v203
	v_mfma_f32_32x32x16_bf16 v[34:49], v[242:245], v[196:199], v[34:49]
	v_add_f32_e32 v167, v167, v0
	ds_read_b128 v[238:241], v180 offset:0
	ds_read_b128 v[242:245], v180 offset:8192
	s_waitcnt lgkmcnt(6)
	v_mfma_f32_32x32x16_bf16 v[18:33], v[246:249], v[196:199], v[18:33]
	v_mfma_f32_32x32x16_bf16 v[2:17], v[250:253], v[196:199], v[2:17]
	ds_read_b128 v[246:249], v179 offset:0
	ds_read_b128 v[250:253], v179 offset:8192
	s_waitcnt vmcnt(6)
	s_add_i32 s50, s50, 64
	s_add_i32 s51, s50, 384
	s_cmp_le_u32 s51, s2
	s_barrier
	s_cbranch_scc1 .Lat2_U_top
